# v54 + nt (streaming) cache policy on the 32 converted-weight stores of the P0 transposes
# baseline (speedup 1.0000x reference)
; #define LAS __attribute__((address_space(3)))
; __device__ __forceinline__ unsigned cvtpk(float lo, float hi) { f32x2 v = {lo, hi}; bf16x2_t b = __builtin_convertvector(v, bf16x2_t); return __builtin_bit_cast(unsigned, b); }
; __device__ __forceinline__ unsigned pack4_fp8(float a, float b, float c, float d) { unsigned w = 0u; w = (unsigned)__builtin_amdgcn_cvt_pk_fp8_f32(a, b, (int)w, false); w = (unsigned)__builtin_amdgcn_cvt_pk_fp8_f32(c, d, (int)w, true); return w; }
; template <bool F8 = false, class Map>
; __device__ __forceinline__ void transpose_item(const float* __restrict__ W, int Nsrc, int K, void* WTv, const float* kscale, float mul, LAS float* scr, int kb, int nb, int lane, const Map map) {
;     ...
;     for (int i = 0; i < 32; ++i) scr[(2 * i + kh) * 33 + (lane & 31)] = v[i];
;     asm volatile("s_waitcnt lgkmcnt(0)" ::: "memory");
;     if constexpr (F8) {
;         unsigned char* WT = (unsigned char*)WTv; const int c = lane & 3;
; #pragma unroll
;         for (int jj = 0; jj < 2; ++jj) { const int n = (lane >> 2) + 16 * jj; const LAS float* s = scr + (16 * c) * 33 + n;
;             u32x4 o; o.x = pack4_fp8(s[0 * 33] * mul, s[1 * 33] * mul, s[2 * 33] * mul, s[3 * 33] * mul); o.y = pack4_fp8(s[4 * 33] * mul, s[5 * 33] * mul, s[6 * 33] * mul, s[7 * 33] * mul);
;             o.z = pack4_fp8(s[8 * 33] * mul, s[9 * 33] * mul, s[10 * 33] * mul, s[11 * 33] * mul); o.w = pack4_fp8(s[12 * 33] * mul, s[13 * 33] * mul, s[14 * 33] * mul, s[15 * 33] * mul);
;             *(u32x4*)(WT + (size_t)(j0 + n) * K + k0 + 16 * c) = o; }
;     } else {
;         bf16_t* WT = (bf16_t*)WTv; const int c = lane & 7;
; #pragma unroll
;         for (int jj = 0; jj < 4; ++jj) { const int n = (lane >> 3) + 8 * jj; const LAS float* s = scr + (8 * c) * 33 + n;
;             u32x4 o; o.x = cvtpk(s[0 * 33], s[1 * 33]); o.y = cvtpk(s[2 * 33], s[3 * 33]); o.z = cvtpk(s[4 * 33], s[5 * 33]); o.w = cvtpk(s[6 * 33], s[7 * 33]);
;             *(u32x4*)(WT + (size_t)(j0 + n) * K + k0 + 8 * c) = o; }
;     }
; __device__ __forceinline__ void p0_prologue(Frame& F) {
;     ...
;             if (r < I_F1) { int kb, nb; blk16(r, 64, kb, nb); transpose_item(F.w_ff1, DFF, D, (bf16_t*)(ws + WS_WFF1T), nullptr, 1.f, scr, kb, nb, lane, MapId{}); continue; } r -= I_F1;
.LBB0_27:
	s_waitcnt vmcnt(0)
	ds_write2_b32 v70, v4, v42 offset1:66
	ds_write2_b32 v70, v43, v39 offset0:132 offset1:198
	v_add_u32_e32 v4, 0x400, v70
	ds_write2_b32 v4, v45, v44 offset0:8 offset1:74
	ds_write2_b32 v4, v47, v46 offset0:140 offset1:206
	v_add_u32_e32 v4, 0x800, v70
	ds_write2_b32 v4, v49, v48 offset0:16 offset1:82
	ds_write2_b32 v4, v51, v50 offset0:148 offset1:214
	v_add_u32_e32 v4, 0xc00, v70
	ds_write2_b32 v4, v53, v52 offset0:24 offset1:90
	ds_write2_b32 v4, v55, v54 offset0:156 offset1:222
	v_add_u32_e32 v4, 0x1000, v70
	ds_write2_b32 v4, v57, v56 offset0:32 offset1:98
	ds_write2_b32 v4, v59, v58 offset0:164 offset1:230
	v_add_u32_e32 v4, 0x1400, v70
	ds_write2_b32 v4, v61, v60 offset0:40 offset1:106
	ds_write2_b32 v4, v63, v62 offset0:172 offset1:238
	v_add_u32_e32 v4, 0x1800, v70
	ds_write2_b32 v4, v65, v64 offset0:48 offset1:114
	ds_write2_b32 v4, v67, v66 offset0:180 offset1:246
	v_add_u32_e32 v4, 0x1c00, v70
	ds_write2_b32 v4, v69, v68 offset0:56 offset1:122
	ds_write2_b32 v4, v84, v83 offset0:188 offset1:254
	s_waitcnt lgkmcnt(0)
	ds_read2_b32 v[42:43], v72 offset0:33 offset1:41
	ds_read2_b32 v[44:45], v72 offset1:8
	ds_read2_b32 v[46:47], v72 offset0:66 offset1:74
	ds_read2_b32 v[48:49], v72 offset0:99 offset1:107
	ds_read2_b32 v[50:51], v72 offset0:132 offset1:140
	ds_read2_b32 v[52:53], v72 offset0:165 offset1:173
	ds_read2_b32 v[54:55], v72 offset0:198 offset1:206
	ds_read2_b32 v[56:57], v72 offset0:231 offset1:239
	v_or_b32_e32 v60, s0, v71
	s_ashr_i32 s11, s10, 31
	v_ashrrev_i32_e32 v61, 31, v60
	v_lshl_add_u64 v[58:59], s[10:11], 1, v[24:25]
	v_lshlrev_b64 v[60:61], 13, v[60:61]
	s_waitcnt lgkmcnt(6)
	v_cvt_pk_bf16_f32 v38, v44, v42
	s_waitcnt lgkmcnt(4)
	v_cvt_pk_bf16_f32 v39, v46, v48
	s_waitcnt lgkmcnt(2)
	v_cvt_pk_bf16_f32 v40, v50, v52
	s_waitcnt lgkmcnt(0)
	v_cvt_pk_bf16_f32 v41, v54, v56
	v_lshl_add_u64 v[60:61], v[58:59], 0, v[60:61]
	v_or_b32_e32 v42, s0, v73
	global_store_dwordx4 v[60:61], v[38:41], off nt
	s_nop 1
	v_cvt_pk_bf16_f32 v38, v45, v43
	v_ashrrev_i32_e32 v43, 31, v42
	v_cvt_pk_bf16_f32 v39, v47, v49
	v_cvt_pk_bf16_f32 v40, v51, v53
	v_cvt_pk_bf16_f32 v41, v55, v57
	v_lshlrev_b64 v[42:43], 13, v[42:43]
	ds_read2_b32 v[44:45], v72 offset0:49 offset1:57
	ds_read2_b32 v[46:47], v72 offset0:16 offset1:24
	ds_read2_b32 v[48:49], v72 offset0:82 offset1:90
	ds_read2_b32 v[50:51], v72 offset0:115 offset1:123
	ds_read2_b32 v[52:53], v72 offset0:148 offset1:156
	ds_read2_b32 v[54:55], v72 offset0:181 offset1:189
	ds_read2_b32 v[56:57], v72 offset0:214 offset1:222
	ds_read2_b32 v[60:61], v72 offset0:247 offset1:255
	v_lshl_add_u64 v[42:43], v[58:59], 0, v[42:43]
	global_store_dwordx4 v[42:43], v[38:41], off nt
	v_or_b32_e32 v42, s0, v74
	v_ashrrev_i32_e32 v43, 31, v42
	v_lshlrev_b64 v[42:43], 13, v[42:43]
	s_waitcnt lgkmcnt(6)
	v_cvt_pk_bf16_f32 v38, v46, v44
	s_waitcnt lgkmcnt(4)
	v_cvt_pk_bf16_f32 v39, v48, v50
	s_waitcnt lgkmcnt(2)
	v_cvt_pk_bf16_f32 v40, v52, v54
	s_waitcnt lgkmcnt(0)
	v_cvt_pk_bf16_f32 v41, v56, v60
	v_lshl_add_u64 v[42:43], v[58:59], 0, v[42:43]
	global_store_dwordx4 v[42:43], v[38:41], off nt
	v_or_b32_e32 v42, s0, v75
	v_ashrrev_i32_e32 v43, 31, v42
	v_lshlrev_b64 v[42:43], 13, v[42:43]
	v_cvt_pk_bf16_f32 v38, v47, v45
	v_cvt_pk_bf16_f32 v39, v49, v51
	v_cvt_pk_bf16_f32 v40, v53, v55
	v_cvt_pk_bf16_f32 v41, v57, v61
	v_lshl_add_u64 v[42:43], v[58:59], 0, v[42:43]
	global_store_dwordx4 v[42:43], v[38:41], off nt
	s_waitcnt lgkmcnt(0)

; #define LAS __attribute__((address_space(3)))
; __device__ __forceinline__ unsigned cvtpk(float lo, float hi) { f32x2 v = {lo, hi}; bf16x2_t b = __builtin_convertvector(v, bf16x2_t); return __builtin_bit_cast(unsigned, b); }
; __device__ __forceinline__ unsigned pack4_fp8(float a, float b, float c, float d) { unsigned w = 0u; w = (unsigned)__builtin_amdgcn_cvt_pk_fp8_f32(a, b, (int)w, false); w = (unsigned)__builtin_amdgcn_cvt_pk_fp8_f32(c, d, (int)w, true); return w; }
; template <bool F8 = false, class Map>
; __device__ __forceinline__ void transpose_item(const float* __restrict__ W, int Nsrc, int K, void* WTv, const float* kscale, float mul, LAS float* scr, int kb, int nb, int lane, const Map map) {
;     ...
;     for (int i = 0; i < 32; ++i) scr[(2 * i + kh) * 33 + (lane & 31)] = v[i];
;     asm volatile("s_waitcnt lgkmcnt(0)" ::: "memory");
;     if constexpr (F8) {
;         unsigned char* WT = (unsigned char*)WTv; const int c = lane & 3;
; #pragma unroll
;         for (int jj = 0; jj < 2; ++jj) { const int n = (lane >> 2) + 16 * jj; const LAS float* s = scr + (16 * c) * 33 + n;
;             u32x4 o; o.x = pack4_fp8(s[0 * 33] * mul, s[1 * 33] * mul, s[2 * 33] * mul, s[3 * 33] * mul); o.y = pack4_fp8(s[4 * 33] * mul, s[5 * 33] * mul, s[6 * 33] * mul, s[7 * 33] * mul);
;             o.z = pack4_fp8(s[8 * 33] * mul, s[9 * 33] * mul, s[10 * 33] * mul, s[11 * 33] * mul); o.w = pack4_fp8(s[12 * 33] * mul, s[13 * 33] * mul, s[14 * 33] * mul, s[15 * 33] * mul);
;             *(u32x4*)(WT + (size_t)(j0 + n) * K + k0 + 16 * c) = o; }
;     } else {
;         bf16_t* WT = (bf16_t*)WTv; const int c = lane & 7;
; #pragma unroll
;         for (int jj = 0; jj < 4; ++jj) { const int n = (lane >> 3) + 8 * jj; const LAS float* s = scr + (8 * c) * 33 + n;
;             u32x4 o; o.x = cvtpk(s[0 * 33], s[1 * 33]); o.y = cvtpk(s[2 * 33], s[3 * 33]); o.z = cvtpk(s[4 * 33], s[5 * 33]); o.w = cvtpk(s[6 * 33], s[7 * 33]);
;             *(u32x4*)(WT + (size_t)(j0 + n) * K + k0 + 8 * c) = o; }
;     }
; __device__ __forceinline__ void p0_prologue(Frame& F) {
;     ...
;             if (r < I_C2) { transpose_item(F.k2, 128, 256, (bf16_t*)(ws + WS_SMALL + 65536), nullptr, 1.f, scr, r / 8, r % 8, lane, MapPad{128}); continue; } r -= I_C2;
.LBB0_102:
	s_or_b64 exec, exec, s[4:5]
	s_waitcnt vmcnt(0)
	ds_write2_b32 v70, v4, v40 offset1:66
	ds_write2_b32 v70, v41, v39 offset0:132 offset1:198
	v_add_u32_e32 v4, 0x400, v70
	ds_write2_b32 v4, v43, v42 offset0:8 offset1:74
	ds_write2_b32 v4, v45, v44 offset0:140 offset1:206
	v_add_u32_e32 v4, 0x800, v70
	ds_write2_b32 v4, v47, v46 offset0:16 offset1:82
	ds_write2_b32 v4, v49, v48 offset0:148 offset1:214
	v_add_u32_e32 v4, 0xc00, v70
	ds_write2_b32 v4, v51, v50 offset0:24 offset1:90
	ds_write2_b32 v4, v53, v52 offset0:156 offset1:222
	v_add_u32_e32 v4, 0x1000, v70
	ds_write2_b32 v4, v55, v54 offset0:32 offset1:98
	ds_write2_b32 v4, v57, v56 offset0:164 offset1:230
	v_add_u32_e32 v4, 0x1400, v70
	ds_write2_b32 v4, v59, v58 offset0:40 offset1:106
	ds_write2_b32 v4, v61, v60 offset0:172 offset1:238
	v_add_u32_e32 v4, 0x1800, v70
	ds_write2_b32 v4, v63, v62 offset0:48 offset1:114
	ds_write2_b32 v4, v65, v64 offset0:180 offset1:246
	v_add_u32_e32 v4, 0x1c00, v70
	ds_write2_b32 v4, v67, v66 offset0:56 offset1:122
	ds_write2_b32 v4, v69, v68 offset0:188 offset1:254
	s_waitcnt lgkmcnt(0)
	ds_read2_b32 v[42:43], v72 offset0:33 offset1:41
	ds_read2_b32 v[44:45], v72 offset1:8
	ds_read2_b32 v[46:47], v72 offset0:66 offset1:74
	ds_read2_b32 v[48:49], v72 offset0:99 offset1:107
	ds_read2_b32 v[50:51], v72 offset0:132 offset1:140
	ds_read2_b32 v[52:53], v72 offset0:165 offset1:173
	ds_read2_b32 v[54:55], v72 offset0:198 offset1:206
	ds_read2_b32 v[56:57], v72 offset0:231 offset1:239
	v_lshl_add_u64 v[58:59], s[0:1], 1, v[6:7]
	s_waitcnt lgkmcnt(6)
	v_cvt_pk_bf16_f32 v38, v44, v42
	s_waitcnt lgkmcnt(4)
	v_cvt_pk_bf16_f32 v39, v46, v48
	s_waitcnt lgkmcnt(2)
	v_cvt_pk_bf16_f32 v40, v50, v52
	s_waitcnt lgkmcnt(0)
	v_cvt_pk_bf16_f32 v41, v54, v56
	v_lshl_add_u64 v[60:61], v[58:59], 0, v[26:27]
	global_store_dwordx4 v[60:61], v[38:41], off nt
	s_mov_b64 s[4:5], 0
	s_nop 0
	v_cvt_pk_bf16_f32 v38, v45, v43
	v_cvt_pk_bf16_f32 v39, v47, v49
	v_cvt_pk_bf16_f32 v40, v51, v53
	v_cvt_pk_bf16_f32 v41, v55, v57
	ds_read2_b32 v[44:45], v72 offset0:49 offset1:57
	ds_read2_b32 v[46:47], v72 offset0:16 offset1:24
	ds_read2_b32 v[48:49], v72 offset0:82 offset1:90
	ds_read2_b32 v[50:51], v72 offset0:115 offset1:123
	ds_read2_b32 v[52:53], v72 offset0:148 offset1:156
	ds_read2_b32 v[54:55], v72 offset0:181 offset1:189
	ds_read2_b32 v[56:57], v72 offset0:214 offset1:222
	ds_read2_b32 v[60:61], v72 offset0:247 offset1:255
	v_lshl_add_u64 v[42:43], v[58:59], 0, v[28:29]
	global_store_dwordx4 v[42:43], v[38:41], off nt
	v_lshl_add_u64 v[42:43], v[58:59], 0, v[30:31]
	s_waitcnt lgkmcnt(6)
	v_cvt_pk_bf16_f32 v38, v46, v44
	s_waitcnt lgkmcnt(4)
	v_cvt_pk_bf16_f32 v39, v48, v50
	s_waitcnt lgkmcnt(2)
	v_cvt_pk_bf16_f32 v40, v52, v54
	s_waitcnt lgkmcnt(0)
	v_cvt_pk_bf16_f32 v41, v56, v60
	global_store_dwordx4 v[42:43], v[38:41], off nt
	v_lshl_add_u64 v[42:43], v[58:59], 0, v[32:33]
	s_nop 0
	v_cvt_pk_bf16_f32 v38, v47, v45
	v_cvt_pk_bf16_f32 v39, v49, v51
	v_cvt_pk_bf16_f32 v40, v53, v55
	v_cvt_pk_bf16_f32 v41, v57, v61
	global_store_dwordx4 v[42:43], v[38:41], off nt
	s_waitcnt lgkmcnt(0)

; #define LAS __attribute__((address_space(3)))
; __device__ __forceinline__ unsigned cvtpk(float lo, float hi) { f32x2 v = {lo, hi}; bf16x2_t b = __builtin_convertvector(v, bf16x2_t); return __builtin_bit_cast(unsigned, b); }
; __device__ __forceinline__ unsigned pack4_fp8(float a, float b, float c, float d) { unsigned w = 0u; w = (unsigned)__builtin_amdgcn_cvt_pk_fp8_f32(a, b, (int)w, false); w = (unsigned)__builtin_amdgcn_cvt_pk_fp8_f32(c, d, (int)w, true); return w; }
; template <bool F8 = false, class Map>
; __device__ __forceinline__ void transpose_item(const float* __restrict__ W, int Nsrc, int K, void* WTv, const float* kscale, float mul, LAS float* scr, int kb, int nb, int lane, const Map map) {
;     ...
;     for (int i = 0; i < 32; ++i) scr[(2 * i + kh) * 33 + (lane & 31)] = v[i];
;     asm volatile("s_waitcnt lgkmcnt(0)" ::: "memory");
;     if constexpr (F8) {
;         unsigned char* WT = (unsigned char*)WTv; const int c = lane & 3;
; #pragma unroll
;         for (int jj = 0; jj < 2; ++jj) { const int n = (lane >> 2) + 16 * jj; const LAS float* s = scr + (16 * c) * 33 + n;
;             u32x4 o; o.x = pack4_fp8(s[0 * 33] * mul, s[1 * 33] * mul, s[2 * 33] * mul, s[3 * 33] * mul); o.y = pack4_fp8(s[4 * 33] * mul, s[5 * 33] * mul, s[6 * 33] * mul, s[7 * 33] * mul);
;             o.z = pack4_fp8(s[8 * 33] * mul, s[9 * 33] * mul, s[10 * 33] * mul, s[11 * 33] * mul); o.w = pack4_fp8(s[12 * 33] * mul, s[13 * 33] * mul, s[14 * 33] * mul, s[15 * 33] * mul);
;             *(u32x4*)(WT + (size_t)(j0 + n) * K + k0 + 16 * c) = o; }
;     } else {
;         bf16_t* WT = (bf16_t*)WTv; const int c = lane & 7;
; #pragma unroll
;         for (int jj = 0; jj < 4; ++jj) { const int n = (lane >> 3) + 8 * jj; const LAS float* s = scr + (8 * c) * 33 + n;
;             u32x4 o; o.x = cvtpk(s[0 * 33], s[1 * 33]); o.y = cvtpk(s[2 * 33], s[3 * 33]); o.z = cvtpk(s[4 * 33], s[5 * 33]); o.w = cvtpk(s[6 * 33], s[7 * 33]);
;             *(u32x4*)(WT + (size_t)(j0 + n) * K + k0 + 8 * c) = o; }
;     }
; __device__ __forceinline__ void p0_prologue(Frame& F) {
;     ...
;             transpose_item(F.v2, 128, 256, (bf16_t*)(ws + WS_SMALL + 196608), nullptr, 1.f, scr, r / 8, r % 8, lane, MapPad{128});
.LBB0_168:
	s_or_b64 exec, exec, s[4:5]
	v_add_u32_e32 v4, 0x400, v70
	s_waitcnt vmcnt(0)
	ds_write2_b32 v70, v38, v39 offset1:66
	ds_write2_b32 v70, v41, v40 offset0:132 offset1:198
	ds_write2_b32 v4, v43, v42 offset0:8 offset1:74
	ds_write2_b32 v4, v45, v44 offset0:140 offset1:206
	v_add_u32_e32 v4, 0x800, v70
	ds_write2_b32 v4, v47, v46 offset0:16 offset1:82
	ds_write2_b32 v4, v49, v48 offset0:148 offset1:214
	v_add_u32_e32 v4, 0xc00, v70
	ds_write2_b32 v4, v51, v50 offset0:24 offset1:90
	ds_write2_b32 v4, v53, v52 offset0:156 offset1:222
	v_add_u32_e32 v4, 0x1000, v70
	ds_write2_b32 v4, v55, v54 offset0:32 offset1:98
	ds_write2_b32 v4, v57, v56 offset0:164 offset1:230
	v_add_u32_e32 v4, 0x1400, v70
	ds_write2_b32 v4, v59, v58 offset0:40 offset1:106
	ds_write2_b32 v4, v61, v60 offset0:172 offset1:238
	v_add_u32_e32 v4, 0x1800, v70
	ds_write2_b32 v4, v63, v62 offset0:48 offset1:114
	ds_write2_b32 v4, v65, v64 offset0:180 offset1:246
	v_add_u32_e32 v4, 0x1c00, v70
	ds_write2_b32 v4, v67, v66 offset0:56 offset1:122
	ds_write2_b32 v4, v69, v68 offset0:188 offset1:254
	s_waitcnt lgkmcnt(0)
	ds_read2_b32 v[42:43], v72 offset0:33 offset1:41
	ds_read2_b32 v[44:45], v72 offset1:8
	ds_read2_b32 v[46:47], v72 offset0:66 offset1:74
	ds_read2_b32 v[48:49], v72 offset0:99 offset1:107
	ds_read2_b32 v[50:51], v72 offset0:132 offset1:140
	ds_read2_b32 v[52:53], v72 offset0:165 offset1:173
	ds_read2_b32 v[54:55], v72 offset0:198 offset1:206
	ds_read2_b32 v[56:57], v72 offset0:231 offset1:239
	v_lshl_add_u64 v[58:59], s[0:1], 1, v[8:9]
	s_waitcnt lgkmcnt(6)
	v_cvt_pk_bf16_f32 v38, v44, v42
	s_waitcnt lgkmcnt(4)
	v_cvt_pk_bf16_f32 v39, v46, v48
	s_waitcnt lgkmcnt(2)
	v_cvt_pk_bf16_f32 v40, v50, v52
	s_waitcnt lgkmcnt(0)
	v_cvt_pk_bf16_f32 v41, v54, v56
	v_lshl_add_u64 v[60:61], v[58:59], 0, v[26:27]
	global_store_dwordx4 v[60:61], v[38:41], off nt
	s_mov_b64 s[4:5], 0
	s_nop 0
	v_cvt_pk_bf16_f32 v38, v45, v43
	v_cvt_pk_bf16_f32 v39, v47, v49
	v_cvt_pk_bf16_f32 v40, v51, v53
	v_cvt_pk_bf16_f32 v41, v55, v57
	ds_read2_b32 v[44:45], v72 offset0:49 offset1:57
	ds_read2_b32 v[46:47], v72 offset0:16 offset1:24
	ds_read2_b32 v[48:49], v72 offset0:82 offset1:90
	ds_read2_b32 v[50:51], v72 offset0:115 offset1:123
	ds_read2_b32 v[52:53], v72 offset0:148 offset1:156
	ds_read2_b32 v[54:55], v72 offset0:181 offset1:189
	ds_read2_b32 v[56:57], v72 offset0:214 offset1:222
	ds_read2_b32 v[60:61], v72 offset0:247 offset1:255
	v_lshl_add_u64 v[42:43], v[58:59], 0, v[28:29]
	global_store_dwordx4 v[42:43], v[38:41], off nt
	v_lshl_add_u64 v[42:43], v[58:59], 0, v[30:31]
	s_waitcnt lgkmcnt(6)
	v_cvt_pk_bf16_f32 v38, v46, v44
	s_waitcnt lgkmcnt(4)
	v_cvt_pk_bf16_f32 v39, v48, v50
	s_waitcnt lgkmcnt(2)
	v_cvt_pk_bf16_f32 v40, v52, v54
	s_waitcnt lgkmcnt(0)
	v_cvt_pk_bf16_f32 v41, v56, v60
	global_store_dwordx4 v[42:43], v[38:41], off nt
	v_lshl_add_u64 v[42:43], v[58:59], 0, v[32:33]
	s_nop 0
	v_cvt_pk_bf16_f32 v38, v47, v45
	v_cvt_pk_bf16_f32 v39, v49, v51
	v_cvt_pk_bf16_f32 v40, v53, v55
	v_cvt_pk_bf16_f32 v41, v57, v61
	global_store_dwordx4 v[42:43], v[38:41], off nt
	s_waitcnt lgkmcnt(0)
	s_branch .LBB0_170

; #define LAS __attribute__((address_space(3)))
; template <bool F8 = false, class Map>
; __device__ __forceinline__ void transpose_item(const float* __restrict__ W, int Nsrc, int K, void* WTv, const float* kscale, float mul, LAS float* scr, int kb, int nb, int lane, const Map map) {
;     const int k0 = 64 * kb, j0 = 32 * nb, sc = map(j0 + (lane & 31)), kh = lane >> 5;
;     float v[32];
; #pragma unroll
;     for (int i = 0; i < 32; ++i) v[i] = sc >= 0 ? W[(size_t)(k0 + 2 * i + kh) * Nsrc + sc] : 0.f;
; __device__ __forceinline__ void p0_prologue(Frame& F) {
;     ...
;             if (r < I_C1) { transpose_item(F.k1, 256, 4096, (bf16_t*)(ws + WS_K1T), nullptr, 1.f, scr, r / 8, r % 8, lane, MapId{}); continue; } r -= I_C1;
.LBB0_170:
	s_andn2_b64 vcc, exec, s[4:5]
	s_cbranch_vccnz .LBB0_172
	s_and_b32 s0, s17, 0xfffc0
	s_and_b32 s4, s15, 0xe0
	s_add_i32 s0, s0, 0xfff4b800
	v_or_b32_e32 v4, s4, v1
	v_or_b32_e32 v38, s0, v3
	v_lshlrev_b32_e32 v4, 2, v4
	v_lshl_add_u64 v[40:41], s[80:81], 0, v[4:5]
	v_or_b32_e32 v4, 2, v38
	v_lshlrev_b64 v[44:45], 10, v[4:5]
	v_or_b32_e32 v4, 4, v38
	v_lshlrev_b64 v[46:47], 10, v[4:5]
	v_or_b32_e32 v4, 6, v38
	v_lshlrev_b64 v[48:49], 10, v[4:5]
	v_or_b32_e32 v4, 8, v38
	v_lshlrev_b64 v[50:51], 10, v[4:5]
	v_or_b32_e32 v4, 10, v38
	v_mov_b32_e32 v39, v5
	v_lshlrev_b64 v[52:53], 10, v[4:5]
	v_or_b32_e32 v4, 12, v38
	v_lshlrev_b64 v[42:43], 10, v[38:39]
	v_lshlrev_b64 v[54:55], 10, v[4:5]
	v_or_b32_e32 v4, 14, v38
	v_lshl_add_u64 v[42:43], v[40:41], 0, v[42:43]
	v_lshlrev_b64 v[56:57], 10, v[4:5]
	v_or_b32_e32 v4, 16, v38
	v_lshl_add_u64 v[44:45], v[40:41], 0, v[44:45]
	v_lshl_add_u64 v[46:47], v[40:41], 0, v[46:47]
	v_lshl_add_u64 v[48:49], v[40:41], 0, v[48:49]
	v_lshl_add_u64 v[50:51], v[40:41], 0, v[50:51]
	v_lshl_add_u64 v[52:53], v[40:41], 0, v[52:53]
	v_lshl_add_u64 v[54:55], v[40:41], 0, v[54:55]
	v_lshl_add_u64 v[56:57], v[40:41], 0, v[56:57]
	global_load_dword v58, v[42:43], off
	global_load_dword v59, v[44:45], off
	global_load_dword v60, v[46:47], off
	global_load_dword v61, v[48:49], off
	global_load_dword v62, v[50:51], off
	global_load_dword v63, v[52:53], off
	global_load_dword v64, v[54:55], off
	global_load_dword v65, v[56:57], off
	v_lshlrev_b64 v[42:43], 10, v[4:5]
	v_or_b32_e32 v4, 18, v38
	v_lshlrev_b64 v[44:45], 10, v[4:5]
	v_or_b32_e32 v4, 20, v38
	v_lshlrev_b64 v[46:47], 10, v[4:5]
	v_or_b32_e32 v4, 22, v38
	v_lshlrev_b64 v[48:49], 10, v[4:5]
	v_or_b32_e32 v4, 24, v38
	v_lshlrev_b64 v[50:51], 10, v[4:5]
	v_or_b32_e32 v4, 26, v38
	v_lshlrev_b64 v[52:53], 10, v[4:5]
	v_or_b32_e32 v4, 28, v38
	v_lshlrev_b64 v[54:55], 10, v[4:5]
	v_or_b32_e32 v4, 30, v38
	v_lshl_add_u64 v[42:43], v[40:41], 0, v[42:43]
	v_lshlrev_b64 v[56:57], 10, v[4:5]
	v_or_b32_e32 v4, 32, v38
	v_lshl_add_u64 v[44:45], v[40:41], 0, v[44:45]
	v_lshl_add_u64 v[46:47], v[40:41], 0, v[46:47]
	v_lshl_add_u64 v[48:49], v[40:41], 0, v[48:49]
	v_lshl_add_u64 v[50:51], v[40:41], 0, v[50:51]
	v_lshl_add_u64 v[52:53], v[40:41], 0, v[52:53]
	v_lshl_add_u64 v[54:55], v[40:41], 0, v[54:55]
	v_lshl_add_u64 v[56:57], v[40:41], 0, v[56:57]
	global_load_dword v66, v[42:43], off
	global_load_dword v67, v[44:45], off
	global_load_dword v68, v[46:47], off
	global_load_dword v69, v[48:49], off
	global_load_dword v83, v[50:51], off
	global_load_dword v84, v[52:53], off
	global_load_dword v85, v[54:55], off
	global_load_dword v86, v[56:57], off
	v_lshlrev_b64 v[42:43], 10, v[4:5]
	v_or_b32_e32 v4, 34, v38
	v_lshlrev_b64 v[44:45], 10, v[4:5]
	v_or_b32_e32 v4, 36, v38
	v_lshlrev_b64 v[46:47], 10, v[4:5]
	v_or_b32_e32 v4, 38, v38
	v_lshlrev_b64 v[48:49], 10, v[4:5]
	v_or_b32_e32 v4, 40, v38
	v_lshlrev_b64 v[50:51], 10, v[4:5]
	v_or_b32_e32 v4, 42, v38
	v_lshlrev_b64 v[52:53], 10, v[4:5]
	v_or_b32_e32 v4, 44, v38
	v_lshlrev_b64 v[54:55], 10, v[4:5]
	v_or_b32_e32 v4, 46, v38
	v_lshlrev_b64 v[56:57], 10, v[4:5]
	v_lshl_add_u64 v[42:43], v[40:41], 0, v[42:43]
	v_lshl_add_u64 v[56:57], v[40:41], 0, v[56:57]
	v_or_b32_e32 v4, 48, v38
	v_lshl_add_u64 v[44:45], v[40:41], 0, v[44:45]
	v_lshl_add_u64 v[46:47], v[40:41], 0, v[46:47]
	v_lshl_add_u64 v[48:49], v[40:41], 0, v[48:49]
	v_lshl_add_u64 v[50:51], v[40:41], 0, v[50:51]
	v_lshl_add_u64 v[52:53], v[40:41], 0, v[52:53]
	v_lshl_add_u64 v[54:55], v[40:41], 0, v[54:55]
	global_load_dword v87, v[42:43], off
	global_load_dword v88, v[44:45], off
	global_load_dword v89, v[46:47], off
	global_load_dword v90, v[48:49], off
	global_load_dword v91, v[50:51], off
	global_load_dword v92, v[52:53], off
	global_load_dword v93, v[54:55], off
	s_nop 0
	global_load_dword v56, v[56:57], off
	v_lshlrev_b64 v[42:43], 10, v[4:5]
	v_or_b32_e32 v4, 50, v38
	v_lshlrev_b64 v[44:45], 10, v[4:5]
	v_or_b32_e32 v4, 52, v38
	v_lshlrev_b64 v[46:47], 10, v[4:5]
	v_or_b32_e32 v4, 54, v38
	v_lshlrev_b64 v[48:49], 10, v[4:5]
	v_or_b32_e32 v4, 56, v38
	v_lshlrev_b64 v[50:51], 10, v[4:5]
	v_or_b32_e32 v4, 58, v38
	v_lshlrev_b64 v[52:53], 10, v[4:5]
	v_or_b32_e32 v4, 60, v38
	v_lshlrev_b64 v[54:55], 10, v[4:5]
	v_or_b32_e32 v4, 62, v38
	v_lshlrev_b64 v[38:39], 10, v[4:5]
	v_lshl_add_u64 v[42:43], v[40:41], 0, v[42:43]
	v_lshl_add_u64 v[44:45], v[40:41], 0, v[44:45]
	v_lshl_add_u64 v[38:39], v[40:41], 0, v[38:39]
	v_lshl_add_u64 v[46:47], v[40:41], 0, v[46:47]
	v_lshl_add_u64 v[48:49], v[40:41], 0, v[48:49]
	v_lshl_add_u64 v[50:51], v[40:41], 0, v[50:51]
	v_lshl_add_u64 v[52:53], v[40:41], 0, v[52:53]
	v_lshl_add_u64 v[54:55], v[40:41], 0, v[54:55]
	global_load_dword v4, v[42:43], off
	global_load_dword v40, v[44:45], off
	global_load_dword v41, v[46:47], off
	s_nop 0
	global_load_dword v42, v[48:49], off
	global_load_dword v43, v[50:51], off
	global_load_dword v44, v[52:53], off
	global_load_dword v45, v[54:55], off
	s_nop 0
	global_load_dword v38, v[38:39], off
	v_add_u32_e32 v39, 0x400, v70
	s_waitcnt vmcnt(30)
; #define LAS __attribute__((address_space(3)))
; __device__ __forceinline__ unsigned cvtpk(float lo, float hi) { f32x2 v = {lo, hi}; bf16x2_t b = __builtin_convertvector(v, bf16x2_t); return __builtin_bit_cast(unsigned, b); }
; __device__ __forceinline__ unsigned pack4_fp8(float a, float b, float c, float d) { unsigned w = 0u; w = (unsigned)__builtin_amdgcn_cvt_pk_fp8_f32(a, b, (int)w, false); w = (unsigned)__builtin_amdgcn_cvt_pk_fp8_f32(c, d, (int)w, true); return w; }
; template <bool F8 = false, class Map>
; __device__ __forceinline__ void transpose_item(const float* __restrict__ W, int Nsrc, int K, void* WTv, const float* kscale, float mul, LAS float* scr, int kb, int nb, int lane, const Map map) {
;     ...
;     for (int i = 0; i < 32; ++i) scr[(2 * i + kh) * 33 + (lane & 31)] = v[i];
;     asm volatile("s_waitcnt lgkmcnt(0)" ::: "memory");
;     if constexpr (F8) {
;         unsigned char* WT = (unsigned char*)WTv; const int c = lane & 3;
; #pragma unroll
;         for (int jj = 0; jj < 2; ++jj) { const int n = (lane >> 2) + 16 * jj; const LAS float* s = scr + (16 * c) * 33 + n;
;             u32x4 o; o.x = pack4_fp8(s[0 * 33] * mul, s[1 * 33] * mul, s[2 * 33] * mul, s[3 * 33] * mul); o.y = pack4_fp8(s[4 * 33] * mul, s[5 * 33] * mul, s[6 * 33] * mul, s[7 * 33] * mul);
;             o.z = pack4_fp8(s[8 * 33] * mul, s[9 * 33] * mul, s[10 * 33] * mul, s[11 * 33] * mul); o.w = pack4_fp8(s[12 * 33] * mul, s[13 * 33] * mul, s[14 * 33] * mul, s[15 * 33] * mul);
;             *(u32x4*)(WT + (size_t)(j0 + n) * K + k0 + 16 * c) = o; }
;     } else {
;         bf16_t* WT = (bf16_t*)WTv; const int c = lane & 7;
; #pragma unroll
;         for (int jj = 0; jj < 4; ++jj) { const int n = (lane >> 3) + 8 * jj; const LAS float* s = scr + (8 * c) * 33 + n;
;             u32x4 o; o.x = cvtpk(s[0 * 33], s[1 * 33]); o.y = cvtpk(s[2 * 33], s[3 * 33]); o.z = cvtpk(s[4 * 33], s[5 * 33]); o.w = cvtpk(s[6 * 33], s[7 * 33]);
;             *(u32x4*)(WT + (size_t)(j0 + n) * K + k0 + 8 * c) = o; }
;     }
	ds_write2_b32 v70, v58, v59 offset1:66
	s_waitcnt vmcnt(28)
	ds_write2_b32 v70, v60, v61 offset0:132 offset1:198
	s_waitcnt vmcnt(26)
	ds_write2_b32 v39, v62, v63 offset0:8 offset1:74
	s_waitcnt vmcnt(24)
	ds_write2_b32 v39, v64, v65 offset0:140 offset1:206
	v_add_u32_e32 v39, 0x800, v70
	s_waitcnt vmcnt(22)
	ds_write2_b32 v39, v66, v67 offset0:16 offset1:82
	s_waitcnt vmcnt(20)
	ds_write2_b32 v39, v68, v69 offset0:148 offset1:214
	v_add_u32_e32 v39, 0xc00, v70
	s_waitcnt vmcnt(18)
	ds_write2_b32 v39, v83, v84 offset0:24 offset1:90
	s_waitcnt vmcnt(16)
	ds_write2_b32 v39, v85, v86 offset0:156 offset1:222
	v_add_u32_e32 v39, 0x1000, v70
	s_waitcnt vmcnt(14)
	ds_write2_b32 v39, v87, v88 offset0:32 offset1:98
	s_waitcnt vmcnt(12)
	ds_write2_b32 v39, v89, v90 offset0:164 offset1:230
	v_add_u32_e32 v39, 0x1400, v70
	s_waitcnt vmcnt(10)
	ds_write2_b32 v39, v91, v92 offset0:40 offset1:106
	s_waitcnt vmcnt(8)
	ds_write2_b32 v39, v93, v56 offset0:172 offset1:238
	v_add_u32_e32 v39, 0x1800, v70
	s_waitcnt vmcnt(6)
	ds_write2_b32 v39, v4, v40 offset0:48 offset1:114
	s_waitcnt vmcnt(4)
	ds_write2_b32 v39, v41, v42 offset0:180 offset1:246
	v_add_u32_e32 v4, 0x1c00, v70
	s_waitcnt vmcnt(2)
	ds_write2_b32 v4, v43, v44 offset0:56 offset1:122
	s_waitcnt vmcnt(0)
	ds_write2_b32 v4, v45, v38 offset0:188 offset1:254
	s_waitcnt lgkmcnt(0)
	ds_read2_b32 v[42:43], v72 offset0:33 offset1:41
	ds_read2_b32 v[44:45], v72 offset1:8
	ds_read2_b32 v[46:47], v72 offset0:66 offset1:74
	ds_read2_b32 v[48:49], v72 offset0:99 offset1:107
	ds_read2_b32 v[50:51], v72 offset0:132 offset1:140
	ds_read2_b32 v[52:53], v72 offset0:165 offset1:173
	ds_read2_b32 v[54:55], v72 offset0:198 offset1:206
	ds_read2_b32 v[56:57], v72 offset0:231 offset1:239
	v_or_b32_e32 v4, s4, v71
	v_lshl_add_u64 v[58:59], s[0:1], 1, v[10:11]
	v_lshlrev_b32_e32 v4, 13, v4
	s_waitcnt lgkmcnt(6)
	v_cvt_pk_bf16_f32 v38, v44, v42
	s_waitcnt lgkmcnt(4)
	v_cvt_pk_bf16_f32 v39, v46, v48
	s_waitcnt lgkmcnt(2)
	v_cvt_pk_bf16_f32 v40, v50, v52
	s_waitcnt lgkmcnt(0)
	v_cvt_pk_bf16_f32 v41, v54, v56
	v_lshl_add_u64 v[60:61], v[58:59], 0, v[4:5]
	global_store_dwordx4 v[60:61], v[38:41], off nt
	v_or_b32_e32 v4, s4, v73
	v_lshlrev_b32_e32 v4, 13, v4
	v_cvt_pk_bf16_f32 v38, v45, v43
	v_cvt_pk_bf16_f32 v39, v47, v49
	v_cvt_pk_bf16_f32 v40, v51, v53
	v_cvt_pk_bf16_f32 v41, v55, v57
	ds_read2_b32 v[44:45], v72 offset0:49 offset1:57
	ds_read2_b32 v[46:47], v72 offset0:16 offset1:24
	ds_read2_b32 v[48:49], v72 offset0:82 offset1:90
	ds_read2_b32 v[50:51], v72 offset0:115 offset1:123
	ds_read2_b32 v[52:53], v72 offset0:148 offset1:156
	ds_read2_b32 v[54:55], v72 offset0:181 offset1:189
	ds_read2_b32 v[56:57], v72 offset0:214 offset1:222
	ds_read2_b32 v[60:61], v72 offset0:247 offset1:255
	v_lshl_add_u64 v[42:43], v[58:59], 0, v[4:5]
	v_or_b32_e32 v4, s4, v74
	v_lshlrev_b32_e32 v4, 13, v4
	global_store_dwordx4 v[42:43], v[38:41], off nt
	v_lshl_add_u64 v[42:43], v[58:59], 0, v[4:5]
	v_or_b32_e32 v4, s4, v75
	s_waitcnt lgkmcnt(6)
	v_cvt_pk_bf16_f32 v38, v46, v44
	s_waitcnt lgkmcnt(4)
	v_cvt_pk_bf16_f32 v39, v48, v50
	s_waitcnt lgkmcnt(2)
	v_cvt_pk_bf16_f32 v40, v52, v54
	s_waitcnt lgkmcnt(0)
	v_cvt_pk_bf16_f32 v41, v56, v60
	v_lshlrev_b32_e32 v4, 13, v4
	global_store_dwordx4 v[42:43], v[38:41], off nt
	v_lshl_add_u64 v[42:43], v[58:59], 0, v[4:5]
	s_nop 0
	v_cvt_pk_bf16_f32 v38, v47, v45
	v_cvt_pk_bf16_f32 v39, v49, v51
	v_cvt_pk_bf16_f32 v40, v53, v55
	v_cvt_pk_bf16_f32 v41, v57, v61
	global_store_dwordx4 v[42:43], v[38:41], off nt
	s_waitcnt lgkmcnt(0)

; #define LAS __attribute__((address_space(3)))
; template <bool F8 = false, class Map>
; __device__ __forceinline__ void transpose_item(const float* __restrict__ W, int Nsrc, int K, void* WTv, const float* kscale, float mul, LAS float* scr, int kb, int nb, int lane, const Map map) {
;     const int k0 = 64 * kb, j0 = 32 * nb, sc = map(j0 + (lane & 31)), kh = lane >> 5;
;     float v[32];
; #pragma unroll
;     for (int i = 0; i < 32; ++i) v[i] = sc >= 0 ? W[(size_t)(k0 + 2 * i + kh) * Nsrc + sc] : 0.f;
; __device__ __forceinline__ void p0_prologue(Frame& F) {
;     ...
;             if (r < I_C1) { transpose_item(F.v1, 256, 4096, (bf16_t*)(ws + WS_V1T), nullptr, 1.f, scr, r / 8, r % 8, lane, MapId{}); continue; } r -= I_C1;
.LBB0_173:
	s_andn2_b64 vcc, exec, s[4:5]
	s_cbranch_vccnz .LBB0_175
	s_and_b32 s0, s17, 0xfffc0
	s_and_b32 s4, s15, 0xe0
	s_add_i32 s0, s0, 0xfff4c800
	v_or_b32_e32 v4, s4, v1
	v_or_b32_e32 v38, s0, v3
	v_lshlrev_b32_e32 v4, 2, v4
	v_lshl_add_u64 v[40:41], s[76:77], 0, v[4:5]
	v_or_b32_e32 v4, 2, v38
	v_lshlrev_b64 v[44:45], 10, v[4:5]
	v_or_b32_e32 v4, 4, v38
	v_lshlrev_b64 v[46:47], 10, v[4:5]
	v_or_b32_e32 v4, 6, v38
	v_lshlrev_b64 v[48:49], 10, v[4:5]
	v_or_b32_e32 v4, 8, v38
	v_lshlrev_b64 v[50:51], 10, v[4:5]
	v_or_b32_e32 v4, 10, v38
	v_mov_b32_e32 v39, v5
	v_lshlrev_b64 v[52:53], 10, v[4:5]
	v_or_b32_e32 v4, 12, v38
	v_lshlrev_b64 v[42:43], 10, v[38:39]
	v_lshlrev_b64 v[54:55], 10, v[4:5]
	v_or_b32_e32 v4, 14, v38
	v_lshl_add_u64 v[42:43], v[40:41], 0, v[42:43]
	v_lshlrev_b64 v[56:57], 10, v[4:5]
	v_or_b32_e32 v4, 16, v38
	v_lshl_add_u64 v[44:45], v[40:41], 0, v[44:45]
	v_lshl_add_u64 v[46:47], v[40:41], 0, v[46:47]
	v_lshl_add_u64 v[48:49], v[40:41], 0, v[48:49]
	v_lshl_add_u64 v[50:51], v[40:41], 0, v[50:51]
	v_lshl_add_u64 v[52:53], v[40:41], 0, v[52:53]
	v_lshl_add_u64 v[54:55], v[40:41], 0, v[54:55]
	v_lshl_add_u64 v[56:57], v[40:41], 0, v[56:57]
	global_load_dword v58, v[42:43], off
	global_load_dword v59, v[44:45], off
	global_load_dword v60, v[46:47], off
	global_load_dword v61, v[48:49], off
	global_load_dword v62, v[50:51], off
	global_load_dword v63, v[52:53], off
	global_load_dword v64, v[54:55], off
	global_load_dword v65, v[56:57], off
	v_lshlrev_b64 v[42:43], 10, v[4:5]
	v_or_b32_e32 v4, 18, v38
	v_lshlrev_b64 v[44:45], 10, v[4:5]
	v_or_b32_e32 v4, 20, v38
	v_lshlrev_b64 v[46:47], 10, v[4:5]
	v_or_b32_e32 v4, 22, v38
	v_lshlrev_b64 v[48:49], 10, v[4:5]
	v_or_b32_e32 v4, 24, v38
	v_lshlrev_b64 v[50:51], 10, v[4:5]
	v_or_b32_e32 v4, 26, v38
	v_lshlrev_b64 v[52:53], 10, v[4:5]
	v_or_b32_e32 v4, 28, v38
	v_lshlrev_b64 v[54:55], 10, v[4:5]
	v_or_b32_e32 v4, 30, v38
	v_lshl_add_u64 v[42:43], v[40:41], 0, v[42:43]
	v_lshlrev_b64 v[56:57], 10, v[4:5]
	v_or_b32_e32 v4, 32, v38
	v_lshl_add_u64 v[44:45], v[40:41], 0, v[44:45]
	v_lshl_add_u64 v[46:47], v[40:41], 0, v[46:47]
	v_lshl_add_u64 v[48:49], v[40:41], 0, v[48:49]
	v_lshl_add_u64 v[50:51], v[40:41], 0, v[50:51]
	v_lshl_add_u64 v[52:53], v[40:41], 0, v[52:53]
	v_lshl_add_u64 v[54:55], v[40:41], 0, v[54:55]
	v_lshl_add_u64 v[56:57], v[40:41], 0, v[56:57]
	global_load_dword v66, v[42:43], off
	global_load_dword v67, v[44:45], off
	global_load_dword v68, v[46:47], off
	global_load_dword v69, v[48:49], off
	global_load_dword v83, v[50:51], off
	global_load_dword v84, v[52:53], off
	global_load_dword v85, v[54:55], off
	global_load_dword v86, v[56:57], off
	v_lshlrev_b64 v[42:43], 10, v[4:5]
	v_or_b32_e32 v4, 34, v38
	v_lshlrev_b64 v[44:45], 10, v[4:5]
	v_or_b32_e32 v4, 36, v38
	v_lshlrev_b64 v[46:47], 10, v[4:5]
	v_or_b32_e32 v4, 38, v38
	v_lshlrev_b64 v[48:49], 10, v[4:5]
	v_or_b32_e32 v4, 40, v38
	v_lshlrev_b64 v[50:51], 10, v[4:5]
	v_or_b32_e32 v4, 42, v38
	v_lshlrev_b64 v[52:53], 10, v[4:5]
	v_or_b32_e32 v4, 44, v38
	v_lshlrev_b64 v[54:55], 10, v[4:5]
	v_or_b32_e32 v4, 46, v38
	v_lshlrev_b64 v[56:57], 10, v[4:5]
	v_lshl_add_u64 v[42:43], v[40:41], 0, v[42:43]
	v_lshl_add_u64 v[56:57], v[40:41], 0, v[56:57]
	v_or_b32_e32 v4, 48, v38
	v_lshl_add_u64 v[44:45], v[40:41], 0, v[44:45]
	v_lshl_add_u64 v[46:47], v[40:41], 0, v[46:47]
	v_lshl_add_u64 v[48:49], v[40:41], 0, v[48:49]
	v_lshl_add_u64 v[50:51], v[40:41], 0, v[50:51]
	v_lshl_add_u64 v[52:53], v[40:41], 0, v[52:53]
	v_lshl_add_u64 v[54:55], v[40:41], 0, v[54:55]
	global_load_dword v87, v[42:43], off
	global_load_dword v88, v[44:45], off
	global_load_dword v89, v[46:47], off
	global_load_dword v90, v[48:49], off
	global_load_dword v91, v[50:51], off
	global_load_dword v92, v[52:53], off
	global_load_dword v93, v[54:55], off
	s_nop 0
	global_load_dword v56, v[56:57], off
	v_lshlrev_b64 v[42:43], 10, v[4:5]
	v_or_b32_e32 v4, 50, v38
	v_lshlrev_b64 v[44:45], 10, v[4:5]
	v_or_b32_e32 v4, 52, v38
	v_lshlrev_b64 v[46:47], 10, v[4:5]
	v_or_b32_e32 v4, 54, v38
	v_lshlrev_b64 v[48:49], 10, v[4:5]
	v_or_b32_e32 v4, 56, v38
	v_lshlrev_b64 v[50:51], 10, v[4:5]
	v_or_b32_e32 v4, 58, v38
	v_lshlrev_b64 v[52:53], 10, v[4:5]
	v_or_b32_e32 v4, 60, v38
	v_lshlrev_b64 v[54:55], 10, v[4:5]
	v_or_b32_e32 v4, 62, v38
	v_lshlrev_b64 v[38:39], 10, v[4:5]
	v_lshl_add_u64 v[42:43], v[40:41], 0, v[42:43]
	v_lshl_add_u64 v[44:45], v[40:41], 0, v[44:45]
	v_lshl_add_u64 v[38:39], v[40:41], 0, v[38:39]
	v_lshl_add_u64 v[46:47], v[40:41], 0, v[46:47]
	v_lshl_add_u64 v[48:49], v[40:41], 0, v[48:49]
	v_lshl_add_u64 v[50:51], v[40:41], 0, v[50:51]
	v_lshl_add_u64 v[52:53], v[40:41], 0, v[52:53]
	v_lshl_add_u64 v[54:55], v[40:41], 0, v[54:55]
	global_load_dword v4, v[42:43], off
	global_load_dword v40, v[44:45], off
	global_load_dword v41, v[46:47], off
	s_nop 0
	global_load_dword v42, v[48:49], off
	global_load_dword v43, v[50:51], off
	global_load_dword v44, v[52:53], off
	global_load_dword v45, v[54:55], off
	s_nop 0
	global_load_dword v38, v[38:39], off
	v_add_u32_e32 v39, 0x400, v70
	s_waitcnt vmcnt(30)
; #define LAS __attribute__((address_space(3)))
; __device__ __forceinline__ unsigned cvtpk(float lo, float hi) { f32x2 v = {lo, hi}; bf16x2_t b = __builtin_convertvector(v, bf16x2_t); return __builtin_bit_cast(unsigned, b); }
; __device__ __forceinline__ unsigned pack4_fp8(float a, float b, float c, float d) { unsigned w = 0u; w = (unsigned)__builtin_amdgcn_cvt_pk_fp8_f32(a, b, (int)w, false); w = (unsigned)__builtin_amdgcn_cvt_pk_fp8_f32(c, d, (int)w, true); return w; }
; template <bool F8 = false, class Map>
; __device__ __forceinline__ void transpose_item(const float* __restrict__ W, int Nsrc, int K, void* WTv, const float* kscale, float mul, LAS float* scr, int kb, int nb, int lane, const Map map) {
;     ...
;     for (int i = 0; i < 32; ++i) scr[(2 * i + kh) * 33 + (lane & 31)] = v[i];
;     asm volatile("s_waitcnt lgkmcnt(0)" ::: "memory");
;     if constexpr (F8) {
;         unsigned char* WT = (unsigned char*)WTv; const int c = lane & 3;
; #pragma unroll
;         for (int jj = 0; jj < 2; ++jj) { const int n = (lane >> 2) + 16 * jj; const LAS float* s = scr + (16 * c) * 33 + n;
;             u32x4 o; o.x = pack4_fp8(s[0 * 33] * mul, s[1 * 33] * mul, s[2 * 33] * mul, s[3 * 33] * mul); o.y = pack4_fp8(s[4 * 33] * mul, s[5 * 33] * mul, s[6 * 33] * mul, s[7 * 33] * mul);
;             o.z = pack4_fp8(s[8 * 33] * mul, s[9 * 33] * mul, s[10 * 33] * mul, s[11 * 33] * mul); o.w = pack4_fp8(s[12 * 33] * mul, s[13 * 33] * mul, s[14 * 33] * mul, s[15 * 33] * mul);
;             *(u32x4*)(WT + (size_t)(j0 + n) * K + k0 + 16 * c) = o; }
;     } else {
;         bf16_t* WT = (bf16_t*)WTv; const int c = lane & 7;
; #pragma unroll
;         for (int jj = 0; jj < 4; ++jj) { const int n = (lane >> 3) + 8 * jj; const LAS float* s = scr + (8 * c) * 33 + n;
;             u32x4 o; o.x = cvtpk(s[0 * 33], s[1 * 33]); o.y = cvtpk(s[2 * 33], s[3 * 33]); o.z = cvtpk(s[4 * 33], s[5 * 33]); o.w = cvtpk(s[6 * 33], s[7 * 33]);
;             *(u32x4*)(WT + (size_t)(j0 + n) * K + k0 + 8 * c) = o; }
;     }
	ds_write2_b32 v70, v58, v59 offset1:66
	s_waitcnt vmcnt(28)
	ds_write2_b32 v70, v60, v61 offset0:132 offset1:198
	s_waitcnt vmcnt(26)
	ds_write2_b32 v39, v62, v63 offset0:8 offset1:74
	s_waitcnt vmcnt(24)
	ds_write2_b32 v39, v64, v65 offset0:140 offset1:206
	v_add_u32_e32 v39, 0x800, v70
	s_waitcnt vmcnt(22)
	ds_write2_b32 v39, v66, v67 offset0:16 offset1:82
	s_waitcnt vmcnt(20)
	ds_write2_b32 v39, v68, v69 offset0:148 offset1:214
	v_add_u32_e32 v39, 0xc00, v70
	s_waitcnt vmcnt(18)
	ds_write2_b32 v39, v83, v84 offset0:24 offset1:90
	s_waitcnt vmcnt(16)
	ds_write2_b32 v39, v85, v86 offset0:156 offset1:222
	v_add_u32_e32 v39, 0x1000, v70
	s_waitcnt vmcnt(14)
	ds_write2_b32 v39, v87, v88 offset0:32 offset1:98
	s_waitcnt vmcnt(12)
	ds_write2_b32 v39, v89, v90 offset0:164 offset1:230
	v_add_u32_e32 v39, 0x1400, v70
	s_waitcnt vmcnt(10)
	ds_write2_b32 v39, v91, v92 offset0:40 offset1:106
	s_waitcnt vmcnt(8)
	ds_write2_b32 v39, v93, v56 offset0:172 offset1:238
	v_add_u32_e32 v39, 0x1800, v70
	s_waitcnt vmcnt(6)
	ds_write2_b32 v39, v4, v40 offset0:48 offset1:114
	s_waitcnt vmcnt(4)
	ds_write2_b32 v39, v41, v42 offset0:180 offset1:246
	v_add_u32_e32 v4, 0x1c00, v70
	s_waitcnt vmcnt(2)
	ds_write2_b32 v4, v43, v44 offset0:56 offset1:122
	s_waitcnt vmcnt(0)
	ds_write2_b32 v4, v45, v38 offset0:188 offset1:254
	s_waitcnt lgkmcnt(0)
	ds_read2_b32 v[42:43], v72 offset0:33 offset1:41
	ds_read2_b32 v[44:45], v72 offset1:8
	ds_read2_b32 v[46:47], v72 offset0:66 offset1:74
	ds_read2_b32 v[48:49], v72 offset0:99 offset1:107
	ds_read2_b32 v[50:51], v72 offset0:132 offset1:140
	ds_read2_b32 v[52:53], v72 offset0:165 offset1:173
	ds_read2_b32 v[54:55], v72 offset0:198 offset1:206
	ds_read2_b32 v[56:57], v72 offset0:231 offset1:239
	v_or_b32_e32 v4, s4, v71
	v_lshl_add_u64 v[58:59], s[0:1], 1, v[12:13]
	v_lshlrev_b32_e32 v4, 13, v4
	s_waitcnt lgkmcnt(6)
	v_cvt_pk_bf16_f32 v38, v44, v42
	s_waitcnt lgkmcnt(4)
	v_cvt_pk_bf16_f32 v39, v46, v48
	s_waitcnt lgkmcnt(2)
	v_cvt_pk_bf16_f32 v40, v50, v52
	s_waitcnt lgkmcnt(0)
	v_cvt_pk_bf16_f32 v41, v54, v56
	v_lshl_add_u64 v[60:61], v[58:59], 0, v[4:5]
	global_store_dwordx4 v[60:61], v[38:41], off nt
	v_or_b32_e32 v4, s4, v73
	v_lshlrev_b32_e32 v4, 13, v4
	v_cvt_pk_bf16_f32 v38, v45, v43
	v_cvt_pk_bf16_f32 v39, v47, v49
	v_cvt_pk_bf16_f32 v40, v51, v53
	v_cvt_pk_bf16_f32 v41, v55, v57
	ds_read2_b32 v[44:45], v72 offset0:49 offset1:57
	ds_read2_b32 v[46:47], v72 offset0:16 offset1:24
	ds_read2_b32 v[48:49], v72 offset0:82 offset1:90
	ds_read2_b32 v[50:51], v72 offset0:115 offset1:123
	ds_read2_b32 v[52:53], v72 offset0:148 offset1:156
	ds_read2_b32 v[54:55], v72 offset0:181 offset1:189
	ds_read2_b32 v[56:57], v72 offset0:214 offset1:222
	ds_read2_b32 v[60:61], v72 offset0:247 offset1:255
	v_lshl_add_u64 v[42:43], v[58:59], 0, v[4:5]
	v_or_b32_e32 v4, s4, v74
	v_lshlrev_b32_e32 v4, 13, v4
	global_store_dwordx4 v[42:43], v[38:41], off nt
	v_lshl_add_u64 v[42:43], v[58:59], 0, v[4:5]
	v_or_b32_e32 v4, s4, v75
	s_waitcnt lgkmcnt(6)
	v_cvt_pk_bf16_f32 v38, v46, v44
	s_waitcnt lgkmcnt(4)
	v_cvt_pk_bf16_f32 v39, v48, v50
	s_waitcnt lgkmcnt(2)
	v_cvt_pk_bf16_f32 v40, v52, v54
	s_waitcnt lgkmcnt(0)
	v_cvt_pk_bf16_f32 v41, v56, v60
	v_lshlrev_b32_e32 v4, 13, v4
	global_store_dwordx4 v[42:43], v[38:41], off nt
	v_lshl_add_u64 v[42:43], v[58:59], 0, v[4:5]
	s_nop 0
	v_cvt_pk_bf16_f32 v38, v47, v45
	v_cvt_pk_bf16_f32 v39, v49, v51
	v_cvt_pk_bf16_f32 v40, v53, v55
	v_cvt_pk_bf16_f32 v41, v57, v61
	global_store_dwordx4 v[42:43], v[38:41], off nt
	s_waitcnt lgkmcnt(0)

; #define LAS __attribute__((address_space(3)))
; __device__ __forceinline__ unsigned pack4_fp8(float a, float b, float c, float d) { unsigned w = 0u; w = (unsigned)__builtin_amdgcn_cvt_pk_fp8_f32(a, b, (int)w, false); w = (unsigned)__builtin_amdgcn_cvt_pk_fp8_f32(c, d, (int)w, true); return w; }
; template <bool F8 = false, class Map>
; __device__ __forceinline__ void transpose_item(const float* __restrict__ W, int Nsrc, int K, void* WTv, const float* kscale, float mul, LAS float* scr, int kb, int nb, int lane, const Map map) {
;     ...
;     for (int i = 0; i < 32; ++i) scr[(2 * i + kh) * 33 + (lane & 31)] = v[i];
;     asm volatile("s_waitcnt lgkmcnt(0)" ::: "memory");
;     if constexpr (F8) {
;         unsigned char* WT = (unsigned char*)WTv; const int c = lane & 3;
; #pragma unroll
;         for (int jj = 0; jj < 2; ++jj) { const int n = (lane >> 2) + 16 * jj; const LAS float* s = scr + (16 * c) * 33 + n;
;             u32x4 o; o.x = pack4_fp8(s[0 * 33] * mul, s[1 * 33] * mul, s[2 * 33] * mul, s[3 * 33] * mul); o.y = pack4_fp8(s[4 * 33] * mul, s[5 * 33] * mul, s[6 * 33] * mul, s[7 * 33] * mul);
;             o.z = pack4_fp8(s[8 * 33] * mul, s[9 * 33] * mul, s[10 * 33] * mul, s[11 * 33] * mul); o.w = pack4_fp8(s[12 * 33] * mul, s[13 * 33] * mul, s[14 * 33] * mul, s[15 * 33] * mul);
;             *(u32x4*)(WT + (size_t)(j0 + n) * K + k0 + 16 * c) = o; }
; __device__ __forceinline__ void p0_prologue(Frame& F) {
;     ...
;             if (r < I_UKV) { transpose_item<FP8_UP>(F.w_ukv, 4096, KVR, (void*)(ws + WS_WUKVT), F.kvn, FP8_UP ? 16.f : 1.f, scr, r / 128, r % 128, lane, MapUkv{}); continue; } r -= I_UKV;
.LBB0_183:
	v_add_u32_e32 v4, 0x400, v70
	s_waitcnt vmcnt(30)
	ds_write2_b32 v70, v38, v39 offset1:66
	s_waitcnt vmcnt(28)
	ds_write2_b32 v70, v42, v43 offset0:132 offset1:198
	s_waitcnt vmcnt(26)
	ds_write2_b32 v4, v40, v41 offset0:8 offset1:74
	s_waitcnt vmcnt(24)
	ds_write2_b32 v4, v44, v45 offset0:140 offset1:206
	v_add_u32_e32 v4, 0x800, v70
	s_waitcnt vmcnt(22)
	ds_write2_b32 v4, v46, v47 offset0:16 offset1:82
	s_waitcnt vmcnt(20)
	ds_write2_b32 v4, v50, v51 offset0:148 offset1:214
	v_add_u32_e32 v4, 0xc00, v70
	s_waitcnt vmcnt(18)
	ds_write2_b32 v4, v48, v49 offset0:24 offset1:90
	s_waitcnt vmcnt(16)
	ds_write2_b32 v4, v52, v53 offset0:156 offset1:222
	v_add_u32_e32 v4, 0x1000, v70
	s_waitcnt vmcnt(14)
	ds_write2_b32 v4, v54, v55 offset0:32 offset1:98
	s_waitcnt vmcnt(12)
	ds_write2_b32 v4, v58, v59 offset0:164 offset1:230
	v_add_u32_e32 v4, 0x1400, v70
	s_waitcnt vmcnt(10)
	ds_write2_b32 v4, v56, v57 offset0:40 offset1:106
	s_waitcnt vmcnt(8)
	ds_write2_b32 v4, v60, v61 offset0:172 offset1:238
	v_add_u32_e32 v4, 0x1800, v70
	s_waitcnt vmcnt(6)
	ds_write2_b32 v4, v62, v63 offset0:48 offset1:114
	s_waitcnt vmcnt(4)
	ds_write2_b32 v4, v68, v69 offset0:180 offset1:246
	v_add_u32_e32 v4, 0x1c00, v70
	s_waitcnt vmcnt(2)
	ds_write2_b32 v4, v66, v67 offset0:56 offset1:122
	s_waitcnt vmcnt(0)
	ds_write2_b32 v4, v64, v65 offset0:188 offset1:254
	s_waitcnt lgkmcnt(0)
	ds_read2_b32 v[42:43], v77 offset1:16
	ds_read2_b32 v[44:45], v77 offset0:33 offset1:49
	ds_read2_b32 v[46:47], v77 offset0:66 offset1:82
	ds_read2_b32 v[50:51], v77 offset0:99 offset1:115
	v_mov_b32_e32 v38, v5
	s_waitcnt lgkmcnt(3)
	v_mul_f32_e32 v4, 0x41800000, v42
	s_waitcnt lgkmcnt(2)
	v_mul_f32_e32 v39, 0x41800000, v44
	v_cvt_pk_fp8_f32 v38, v4, v39
	ds_read2_b32 v[52:53], v77 offset0:132 offset1:148
	ds_read2_b32 v[54:55], v77 offset0:165 offset1:181
	ds_read2_b32 v[56:57], v77 offset0:198 offset1:214
	s_waitcnt lgkmcnt(4)
	v_mul_f32_e32 v40, 0x41800000, v46
	s_waitcnt lgkmcnt(3)
	v_mul_f32_e32 v4, 0x41800000, v50
	v_cvt_pk_fp8_f32 v38, v40, v4 op_sel:[0,0,1]
	s_waitcnt lgkmcnt(2)
	v_mul_f32_e32 v4, 0x41800000, v52
	s_waitcnt lgkmcnt(1)
	v_mul_f32_e32 v40, 0x41800000, v54
	v_mov_b32_e32 v39, v5
	ds_read2_b32 v[58:59], v77 offset0:231 offset1:247
	v_cvt_pk_fp8_f32 v39, v4, v40
	v_add_u32_e32 v4, 0x400, v77
	ds_read2_b32 v[60:61], v4 offset0:8 offset1:24
	ds_read2_b32 v[62:63], v4 offset0:41 offset1:57
	ds_read2_b32 v[64:65], v4 offset0:74 offset1:90
	ds_read2_b32 v[66:67], v4 offset0:107 offset1:123
	ds_read2_b32 v[68:69], v4 offset0:140 offset1:156
	ds_read2_b32 v[84:85], v4 offset0:173 offset1:189
	s_waitcnt lgkmcnt(7)
	v_mul_f32_e32 v41, 0x41800000, v56
	s_waitcnt lgkmcnt(6)
	v_mul_f32_e32 v40, 0x41800000, v58
	v_cvt_pk_fp8_f32 v39, v41, v40 op_sel:[0,0,1]
	s_waitcnt lgkmcnt(5)
	v_mul_f32_e32 v41, 0x41800000, v60
	s_waitcnt lgkmcnt(4)
	v_mul_f32_e32 v42, 0x41800000, v62
	v_mov_b32_e32 v40, v5
	ds_read2_b32 v[86:87], v4 offset0:206 offset1:222
	ds_read2_b32 v[88:89], v4 offset0:239 offset1:255
	v_cvt_pk_fp8_f32 v40, v41, v42
	s_waitcnt lgkmcnt(3)
	v_mul_f32_e32 v42, 0x41800000, v68
	s_waitcnt lgkmcnt(2)
	v_mul_f32_e32 v50, 0x41800000, v84
	v_mov_b32_e32 v41, v5
	v_cvt_pk_fp8_f32 v41, v42, v50
	v_mul_f32_e32 v44, 0x41800000, v64
	v_mul_f32_e32 v46, 0x41800000, v66
	s_waitcnt lgkmcnt(1)
	v_mul_f32_e32 v4, 0x41800000, v86
	s_waitcnt lgkmcnt(0)
	v_mul_f32_e32 v42, 0x41800000, v88
	v_cvt_pk_fp8_f32 v40, v44, v46 op_sel:[0,0,1]
	v_cvt_pk_fp8_f32 v41, v4, v42 op_sel:[0,0,1]
	v_or_b32_e32 v4, s10, v76
	v_lshl_add_u64 v[48:49], v[14:15], 0, s[0:1]
	v_lshlrev_b32_e32 v4, 9, v4
	v_lshl_add_u64 v[90:91], v[48:49], 0, v[4:5]
	global_store_dwordx4 v[90:91], v[38:41], off nt
	v_mul_f32_e32 v4, 0x41800000, v43
	v_mul_f32_e32 v42, 0x41800000, v55
	v_mul_f32_e32 v39, 0x41800000, v45
	v_mov_b32_e32 v38, v5
	v_cvt_pk_fp8_f32 v38, v4, v39
	v_mul_f32_e32 v4, 0x41800000, v53
	v_mov_b32_e32 v39, v5
	v_cvt_pk_fp8_f32 v39, v4, v42
	v_mul_f32_e32 v40, 0x41800000, v47
	v_mul_f32_e32 v41, 0x41800000, v51
	v_cvt_pk_fp8_f32 v38, v40, v41 op_sel:[0,0,1]
	v_mul_f32_e32 v4, 0x41800000, v57
	v_mul_f32_e32 v40, 0x41800000, v59
	v_cvt_pk_fp8_f32 v39, v4, v40 op_sel:[0,0,1]
	v_mul_f32_e32 v4, 0x41800000, v61
	v_mul_f32_e32 v41, 0x41800000, v63
	v_mov_b32_e32 v40, v5
	v_cvt_pk_fp8_f32 v40, v4, v41
	v_mul_f32_e32 v4, 0x41800000, v69
	v_mul_f32_e32 v44, 0x41800000, v85
	v_mov_b32_e32 v41, v5
	v_cvt_pk_fp8_f32 v41, v4, v44
	v_mul_f32_e32 v42, 0x41800000, v65
	v_mul_f32_e32 v43, 0x41800000, v67
	v_cvt_pk_fp8_f32 v40, v42, v43 op_sel:[0,0,1]
	v_mul_f32_e32 v4, 0x41800000, v87
	v_mul_f32_e32 v42, 0x41800000, v89
	v_cvt_pk_fp8_f32 v41, v4, v42 op_sel:[0,0,1]
	v_or_b32_e32 v4, s10, v78
	v_lshlrev_b32_e32 v4, 9, v4
	v_lshl_add_u64 v[42:43], v[48:49], 0, v[4:5]
	global_store_dwordx4 v[42:43], v[38:41], off nt
	s_waitcnt lgkmcnt(0)

; #define LAS __attribute__((address_space(3)))
; __device__ __forceinline__ unsigned pack4_fp8(float a, float b, float c, float d) { unsigned w = 0u; w = (unsigned)__builtin_amdgcn_cvt_pk_fp8_f32(a, b, (int)w, false); w = (unsigned)__builtin_amdgcn_cvt_pk_fp8_f32(c, d, (int)w, true); return w; }
; template <bool F8 = false, class Map>
; __device__ __forceinline__ void transpose_item(const float* __restrict__ W, int Nsrc, int K, void* WTv, const float* kscale, float mul, LAS float* scr, int kb, int nb, int lane, const Map map) {
;     ...
;     for (int i = 0; i < 32; ++i) scr[(2 * i + kh) * 33 + (lane & 31)] = v[i];
;     asm volatile("s_waitcnt lgkmcnt(0)" ::: "memory");
;     if constexpr (F8) {
;         unsigned char* WT = (unsigned char*)WTv; const int c = lane & 3;
; #pragma unroll
;         for (int jj = 0; jj < 2; ++jj) { const int n = (lane >> 2) + 16 * jj; const LAS float* s = scr + (16 * c) * 33 + n;
;             u32x4 o; o.x = pack4_fp8(s[0 * 33] * mul, s[1 * 33] * mul, s[2 * 33] * mul, s[3 * 33] * mul); o.y = pack4_fp8(s[4 * 33] * mul, s[5 * 33] * mul, s[6 * 33] * mul, s[7 * 33] * mul);
;             o.z = pack4_fp8(s[8 * 33] * mul, s[9 * 33] * mul, s[10 * 33] * mul, s[11 * 33] * mul); o.w = pack4_fp8(s[12 * 33] * mul, s[13 * 33] * mul, s[14 * 33] * mul, s[15 * 33] * mul);
;             *(u32x4*)(WT + (size_t)(j0 + n) * K + k0 + 16 * c) = o; }
; __device__ __forceinline__ void p0_prologue(Frame& F) {
;     ...
;             if (r < I_UQ) { transpose_item<FP8_UP>(F.w_uq, 3072, QR, (void*)(ws + WS_WUQT), F.qn, FP8_UP ? 32.f : 1.f, scr, r / 96, r % 96, lane, MapUq{}); continue; } r -= I_UQ;
.LBB0_194:
	v_add_u32_e32 v4, 0x400, v70
	s_waitcnt vmcnt(30)
	ds_write2_b32 v70, v38, v39 offset1:66
	s_waitcnt vmcnt(28)
	ds_write2_b32 v70, v42, v43 offset0:132 offset1:198
	s_waitcnt vmcnt(26)
	ds_write2_b32 v4, v40, v41 offset0:8 offset1:74
	s_waitcnt vmcnt(24)
	ds_write2_b32 v4, v44, v45 offset0:140 offset1:206
	v_add_u32_e32 v4, 0x800, v70
	s_waitcnt vmcnt(22)
	ds_write2_b32 v4, v46, v47 offset0:16 offset1:82
	s_waitcnt vmcnt(20)
	ds_write2_b32 v4, v50, v51 offset0:148 offset1:214
	v_add_u32_e32 v4, 0xc00, v70
	s_waitcnt vmcnt(18)
	ds_write2_b32 v4, v48, v49 offset0:24 offset1:90
	s_waitcnt vmcnt(16)
	ds_write2_b32 v4, v52, v53 offset0:156 offset1:222
	v_add_u32_e32 v4, 0x1000, v70
	s_waitcnt vmcnt(14)
	ds_write2_b32 v4, v54, v55 offset0:32 offset1:98
	s_waitcnt vmcnt(12)
	ds_write2_b32 v4, v58, v59 offset0:164 offset1:230
	v_add_u32_e32 v4, 0x1400, v70
	s_waitcnt vmcnt(10)
	ds_write2_b32 v4, v56, v57 offset0:40 offset1:106
	s_waitcnt vmcnt(8)
	ds_write2_b32 v4, v60, v61 offset0:172 offset1:238
	v_add_u32_e32 v4, 0x1800, v70
	s_waitcnt vmcnt(6)
	ds_write2_b32 v4, v62, v63 offset0:48 offset1:114
	s_waitcnt vmcnt(4)
	ds_write2_b32 v4, v68, v69 offset0:180 offset1:246
	v_add_u32_e32 v4, 0x1c00, v70
	s_waitcnt vmcnt(2)
	ds_write2_b32 v4, v66, v67 offset0:56 offset1:122
	s_waitcnt vmcnt(0)
	ds_write2_b32 v4, v64, v65 offset0:188 offset1:254
	s_waitcnt lgkmcnt(0)
	ds_read2_b32 v[42:43], v77 offset1:16
	ds_read2_b32 v[44:45], v77 offset0:33 offset1:49
	ds_read2_b32 v[46:47], v77 offset0:66 offset1:82
	ds_read2_b32 v[50:51], v77 offset0:99 offset1:115
	v_mov_b32_e32 v38, v5
	s_waitcnt lgkmcnt(3)
	v_mul_f32_e32 v4, 0x42000000, v42
	s_waitcnt lgkmcnt(2)
	v_mul_f32_e32 v39, 0x42000000, v44
	v_cvt_pk_fp8_f32 v38, v4, v39
	ds_read2_b32 v[52:53], v77 offset0:132 offset1:148
	ds_read2_b32 v[54:55], v77 offset0:165 offset1:181
	ds_read2_b32 v[56:57], v77 offset0:198 offset1:214
	s_waitcnt lgkmcnt(4)
	v_mul_f32_e32 v40, 0x42000000, v46
	s_waitcnt lgkmcnt(3)
	v_mul_f32_e32 v4, 0x42000000, v50
	v_cvt_pk_fp8_f32 v38, v40, v4 op_sel:[0,0,1]
	s_waitcnt lgkmcnt(2)
	v_mul_f32_e32 v4, 0x42000000, v52
	s_waitcnt lgkmcnt(1)
	v_mul_f32_e32 v40, 0x42000000, v54
	v_mov_b32_e32 v39, v5
	ds_read2_b32 v[58:59], v77 offset0:231 offset1:247
	v_cvt_pk_fp8_f32 v39, v4, v40
	v_add_u32_e32 v4, 0x400, v77
	ds_read2_b32 v[60:61], v4 offset0:8 offset1:24
	ds_read2_b32 v[62:63], v4 offset0:41 offset1:57
	ds_read2_b32 v[64:65], v4 offset0:74 offset1:90
	ds_read2_b32 v[66:67], v4 offset0:107 offset1:123
	ds_read2_b32 v[68:69], v4 offset0:140 offset1:156
	ds_read2_b32 v[84:85], v4 offset0:173 offset1:189
	s_waitcnt lgkmcnt(7)
	v_mul_f32_e32 v41, 0x42000000, v56
	s_waitcnt lgkmcnt(6)
	v_mul_f32_e32 v40, 0x42000000, v58
	v_cvt_pk_fp8_f32 v39, v41, v40 op_sel:[0,0,1]
	s_waitcnt lgkmcnt(5)
	v_mul_f32_e32 v41, 0x42000000, v60
	s_waitcnt lgkmcnt(4)
	v_mul_f32_e32 v42, 0x42000000, v62
	v_mov_b32_e32 v40, v5
	ds_read2_b32 v[86:87], v4 offset0:206 offset1:222
	ds_read2_b32 v[88:89], v4 offset0:239 offset1:255
	v_cvt_pk_fp8_f32 v40, v41, v42
	s_waitcnt lgkmcnt(3)
	v_mul_f32_e32 v42, 0x42000000, v68
	s_waitcnt lgkmcnt(2)
	v_mul_f32_e32 v50, 0x42000000, v84
	v_mov_b32_e32 v41, v5
	v_cvt_pk_fp8_f32 v41, v42, v50
	v_mul_f32_e32 v44, 0x42000000, v64
	v_mul_f32_e32 v46, 0x42000000, v66
	s_waitcnt lgkmcnt(1)
	v_mul_f32_e32 v4, 0x42000000, v86
	s_waitcnt lgkmcnt(0)
	v_mul_f32_e32 v42, 0x42000000, v88
	v_cvt_pk_fp8_f32 v40, v44, v46 op_sel:[0,0,1]
	v_cvt_pk_fp8_f32 v41, v4, v42 op_sel:[0,0,1]
	v_or_b32_e32 v4, s10, v76
	v_lshl_add_u64 v[48:49], v[16:17], 0, s[0:1]
	v_mul_u32_u24_e32 v4, 0x600, v4
	v_lshl_add_u64 v[90:91], v[48:49], 0, v[4:5]
	global_store_dwordx4 v[90:91], v[38:41], off nt
	v_mul_f32_e32 v4, 0x42000000, v43
	v_mul_f32_e32 v42, 0x42000000, v55
	v_mul_f32_e32 v39, 0x42000000, v45
	v_mov_b32_e32 v38, v5
	v_cvt_pk_fp8_f32 v38, v4, v39
	v_mul_f32_e32 v4, 0x42000000, v53
	v_mov_b32_e32 v39, v5
	v_cvt_pk_fp8_f32 v39, v4, v42
	v_mul_f32_e32 v40, 0x42000000, v47
	v_mul_f32_e32 v41, 0x42000000, v51
	v_cvt_pk_fp8_f32 v38, v40, v41 op_sel:[0,0,1]
	v_mul_f32_e32 v4, 0x42000000, v57
	v_mul_f32_e32 v40, 0x42000000, v59
	v_cvt_pk_fp8_f32 v39, v4, v40 op_sel:[0,0,1]
	v_mul_f32_e32 v4, 0x42000000, v61
	v_mul_f32_e32 v41, 0x42000000, v63
	v_mov_b32_e32 v40, v5
	v_cvt_pk_fp8_f32 v40, v4, v41
	v_mul_f32_e32 v4, 0x42000000, v69
	v_mul_f32_e32 v44, 0x42000000, v85
	v_mov_b32_e32 v41, v5
	v_cvt_pk_fp8_f32 v41, v4, v44
	v_mul_f32_e32 v42, 0x42000000, v65
	v_mul_f32_e32 v43, 0x42000000, v67
	v_cvt_pk_fp8_f32 v40, v42, v43 op_sel:[0,0,1]
	v_mul_f32_e32 v4, 0x42000000, v87
	v_mul_f32_e32 v42, 0x42000000, v89
	v_cvt_pk_fp8_f32 v41, v4, v42 op_sel:[0,0,1]
	v_or_b32_e32 v4, s10, v78
	v_mul_u32_u24_e32 v4, 0x600, v4
	v_lshl_add_u64 v[42:43], v[48:49], 0, v[4:5]
	global_store_dwordx4 v[42:43], v[38:41], off nt
	s_waitcnt lgkmcnt(0)

; #define LAS __attribute__((address_space(3)))
; template <bool F8 = false, class Map>
; __device__ __forceinline__ void transpose_item(const float* __restrict__ W, int Nsrc, int K, void* WTv, const float* kscale, float mul, LAS float* scr, int kb, int nb, int lane, const Map map) {
;     const int k0 = 64 * kb, j0 = 32 * nb, sc = map(j0 + (lane & 31)), kh = lane >> 5;
;     float v[32];
; #pragma unroll
;     for (int i = 0; i < 32; ++i) v[i] = sc >= 0 ? W[(size_t)(k0 + 2 * i + kh) * Nsrc + sc] : 0.f;
; __device__ __forceinline__ void p0_prologue(Frame& F) {
;     ...
;             if (r < I_OUT) { int kb, nb; blk16(r, 64, kb, nb); transpose_item<FP8_OUT>(F.w_out, D, D, (void*)(ws + WS_WOUTT), nullptr, FP8_OUT ? 64.f : 1.f, scr, kb, nb, lane, MapId{}); continue; } r -= I_OUT;
.LBB0_196:
	s_andn2_b64 vcc, exec, s[4:5]
	s_cbranch_vccnz .LBB0_198
	s_add_i32 s0, s58, 0xfffec600
	s_lshr_b32 s4, s0, 4
	s_and_b32 s4, s4, 48
	s_bfe_u32 s5, s58, 0x40004
	s_lshr_b32 s0, s0, 6
	s_or_b32 s4, s4, s5
	s_and_b32 s0, s0, 0x3f0
	s_and_b32 s5, s58, 15
	s_or_b32 s5, s0, s5
	s_lshl_b32 s0, s4, 6
	s_lshl_b32 s4, s5, 5
	v_or_b32_e32 v4, s4, v1
	v_readlane_b32 s60, v245, 10
	v_or_b32_e32 v40, s0, v3
	v_lshlrev_b32_e32 v4, 2, v4
	v_readlane_b32 s61, v245, 11
	v_readlane_b32 s62, v245, 12
	v_readlane_b32 s63, v245, 13
	v_lshl_add_u64 v[38:39], s[60:61], 0, v[4:5]
	v_lshlrev_b32_e32 v4, 14, v40
	v_lshl_add_u64 v[38:39], v[38:39], 0, v[4:5]
	v_add_co_u32_e32 v40, vcc, s22, v38
	v_readlane_b32 s64, v245, 14
	s_nop 0
	v_addc_co_u32_e32 v41, vcc, 0, v39, vcc
	v_add_co_u32_e32 v42, vcc, s23, v38
	v_readlane_b32 s65, v245, 15
	s_nop 0
	v_addc_co_u32_e32 v43, vcc, 0, v39, vcc
	v_add_co_u32_e32 v44, vcc, s24, v38
	v_readlane_b32 s66, v245, 16
	s_nop 0
	v_addc_co_u32_e32 v45, vcc, 0, v39, vcc
	v_add_co_u32_e32 v46, vcc, s25, v38
	v_readlane_b32 s67, v245, 17
	s_nop 0
	v_addc_co_u32_e32 v47, vcc, 0, v39, vcc
	v_add_co_u32_e32 v48, vcc, s26, v38
	v_readlane_b32 s68, v245, 18
	s_nop 0
	v_addc_co_u32_e32 v49, vcc, 0, v39, vcc
	v_add_co_u32_e32 v50, vcc, s27, v38
	v_readlane_b32 s69, v245, 19
	s_nop 0
	v_addc_co_u32_e32 v51, vcc, 0, v39, vcc
	v_add_co_u32_e32 v52, vcc, s28, v38
	v_readlane_b32 s70, v245, 20
	s_nop 0
	v_addc_co_u32_e32 v53, vcc, 0, v39, vcc
	global_load_dword v4, v[38:39], off
	global_load_dword v56, v[40:41], off
	global_load_dword v57, v[42:43], off
	global_load_dword v58, v[44:45], off
	global_load_dword v59, v[46:47], off
	global_load_dword v60, v[48:49], off
	global_load_dword v61, v[50:51], off
	global_load_dword v62, v[52:53], off
	v_add_co_u32_e32 v40, vcc, s29, v38
	v_readlane_b32 s71, v245, 21
	s_nop 0
	v_addc_co_u32_e32 v41, vcc, 0, v39, vcc
	v_add_co_u32_e32 v42, vcc, s33, v38
	v_readlane_b32 s72, v245, 22
	s_nop 0
	v_addc_co_u32_e32 v43, vcc, 0, v39, vcc
	v_add_co_u32_e32 v44, vcc, s34, v38
	v_readlane_b32 s73, v245, 23
	s_nop 0
	v_addc_co_u32_e32 v45, vcc, 0, v39, vcc
	v_add_co_u32_e32 v46, vcc, s36, v38
	v_readlane_b32 s74, v245, 24
	s_nop 0
	v_addc_co_u32_e32 v47, vcc, 0, v39, vcc
	v_add_co_u32_e32 v48, vcc, s38, v38
	v_readlane_b32 s75, v245, 25
	s_nop 0
	v_addc_co_u32_e32 v49, vcc, 0, v39, vcc
	v_add_co_u32_e32 v50, vcc, s39, v38
	s_nop 1
	v_addc_co_u32_e32 v51, vcc, 0, v39, vcc
	v_add_co_u32_e32 v52, vcc, s40, v38
	s_nop 1
	v_addc_co_u32_e32 v53, vcc, 0, v39, vcc
	v_add_co_u32_e32 v54, vcc, s41, v38
	s_nop 1
	v_addc_co_u32_e32 v55, vcc, 0, v39, vcc
	global_load_dword v63, v[40:41], off
	global_load_dword v64, v[42:43], off
	global_load_dword v65, v[44:45], off
	global_load_dword v66, v[46:47], off
	global_load_dword v67, v[48:49], off
	global_load_dword v68, v[50:51], off
	global_load_dword v69, v[52:53], off
	global_load_dword v83, v[54:55], off
	v_add_co_u32_e32 v40, vcc, s42, v38
	s_nop 1
	v_addc_co_u32_e32 v41, vcc, 0, v39, vcc
	v_add_co_u32_e32 v42, vcc, s43, v38
	s_nop 1
	v_addc_co_u32_e32 v43, vcc, 0, v39, vcc
	v_add_co_u32_e32 v44, vcc, s44, v38
	s_nop 1
	v_addc_co_u32_e32 v45, vcc, 0, v39, vcc
	v_add_co_u32_e32 v46, vcc, s45, v38
	s_nop 1
	v_addc_co_u32_e32 v47, vcc, 0, v39, vcc
	v_add_co_u32_e32 v48, vcc, s46, v38
	s_nop 1
	v_addc_co_u32_e32 v49, vcc, 0, v39, vcc
	v_add_co_u32_e32 v50, vcc, s47, v38
	s_nop 1
	v_addc_co_u32_e32 v51, vcc, 0, v39, vcc
	v_add_co_u32_e32 v52, vcc, s48, v38
	s_nop 1
	v_addc_co_u32_e32 v53, vcc, 0, v39, vcc
	v_add_co_u32_e32 v54, vcc, s49, v38
	s_nop 1
	v_addc_co_u32_e32 v55, vcc, 0, v39, vcc
	global_load_dword v84, v[40:41], off
	global_load_dword v85, v[42:43], off
	global_load_dword v86, v[44:45], off
	global_load_dword v87, v[46:47], off
	global_load_dword v88, v[48:49], off
	global_load_dword v89, v[50:51], off
	global_load_dword v90, v[52:53], off
	s_nop 0
	global_load_dword v54, v[54:55], off
	v_add_co_u32_e32 v40, vcc, s50, v38
	s_nop 1
	v_addc_co_u32_e32 v41, vcc, 0, v39, vcc
	v_add_co_u32_e32 v42, vcc, s51, v38
	s_nop 1
	v_addc_co_u32_e32 v43, vcc, 0, v39, vcc
	v_add_co_u32_e32 v44, vcc, s52, v38
	s_nop 1
	v_addc_co_u32_e32 v45, vcc, 0, v39, vcc
	v_add_co_u32_e32 v46, vcc, s53, v38
	s_nop 1
	v_addc_co_u32_e32 v47, vcc, 0, v39, vcc
	v_add_co_u32_e32 v48, vcc, s54, v38
	s_nop 1
	v_addc_co_u32_e32 v49, vcc, 0, v39, vcc
	v_add_co_u32_e32 v50, vcc, s55, v38
	s_nop 1
	v_addc_co_u32_e32 v51, vcc, 0, v39, vcc
	v_add_co_u32_e32 v52, vcc, s56, v38
	s_nop 1
	v_addc_co_u32_e32 v53, vcc, 0, v39, vcc
	v_add_co_u32_e32 v38, vcc, s57, v38
	s_nop 1
	v_addc_co_u32_e32 v39, vcc, 0, v39, vcc
	global_load_dword v40, v[40:41], off
	s_nop 0
	global_load_dword v41, v[42:43], off
	s_nop 0
	global_load_dword v42, v[44:45], off
	global_load_dword v43, v[46:47], off
	s_nop 0
	global_load_dword v44, v[48:49], off
	global_load_dword v45, v[50:51], off
	global_load_dword v46, v[52:53], off
	s_nop 0
	global_load_dword v38, v[38:39], off
	s_waitcnt vmcnt(30)
; #define LAS __attribute__((address_space(3)))
; __device__ __forceinline__ unsigned pack4_fp8(float a, float b, float c, float d) { unsigned w = 0u; w = (unsigned)__builtin_amdgcn_cvt_pk_fp8_f32(a, b, (int)w, false); w = (unsigned)__builtin_amdgcn_cvt_pk_fp8_f32(c, d, (int)w, true); return w; }
; template <bool F8 = false, class Map>
; __device__ __forceinline__ void transpose_item(const float* __restrict__ W, int Nsrc, int K, void* WTv, const float* kscale, float mul, LAS float* scr, int kb, int nb, int lane, const Map map) {
;     ...
;     for (int i = 0; i < 32; ++i) scr[(2 * i + kh) * 33 + (lane & 31)] = v[i];
;     asm volatile("s_waitcnt lgkmcnt(0)" ::: "memory");
;     if constexpr (F8) {
;         unsigned char* WT = (unsigned char*)WTv; const int c = lane & 3;
; #pragma unroll
;         for (int jj = 0; jj < 2; ++jj) { const int n = (lane >> 2) + 16 * jj; const LAS float* s = scr + (16 * c) * 33 + n;
;             u32x4 o; o.x = pack4_fp8(s[0 * 33] * mul, s[1 * 33] * mul, s[2 * 33] * mul, s[3 * 33] * mul); o.y = pack4_fp8(s[4 * 33] * mul, s[5 * 33] * mul, s[6 * 33] * mul, s[7 * 33] * mul);
;             o.z = pack4_fp8(s[8 * 33] * mul, s[9 * 33] * mul, s[10 * 33] * mul, s[11 * 33] * mul); o.w = pack4_fp8(s[12 * 33] * mul, s[13 * 33] * mul, s[14 * 33] * mul, s[15 * 33] * mul);
;             *(u32x4*)(WT + (size_t)(j0 + n) * K + k0 + 16 * c) = o; }
	ds_write2_b32 v70, v4, v56 offset1:66
	s_waitcnt vmcnt(28)
	ds_write2_b32 v70, v57, v58 offset0:132 offset1:198
	v_add_u32_e32 v4, 0x400, v70
	s_waitcnt vmcnt(26)
	ds_write2_b32 v4, v59, v60 offset0:8 offset1:74
	s_waitcnt vmcnt(24)
	ds_write2_b32 v4, v61, v62 offset0:140 offset1:206
	v_add_u32_e32 v4, 0x800, v70
	s_waitcnt vmcnt(22)
	ds_write2_b32 v4, v63, v64 offset0:16 offset1:82
	s_waitcnt vmcnt(20)
	ds_write2_b32 v4, v65, v66 offset0:148 offset1:214
	v_add_u32_e32 v4, 0xc00, v70
	s_waitcnt vmcnt(18)
	ds_write2_b32 v4, v67, v68 offset0:24 offset1:90
	s_waitcnt vmcnt(16)
	ds_write2_b32 v4, v69, v83 offset0:156 offset1:222
	v_add_u32_e32 v4, 0x1000, v70
	s_waitcnt vmcnt(14)
	ds_write2_b32 v4, v84, v85 offset0:32 offset1:98
	s_waitcnt vmcnt(12)
	ds_write2_b32 v4, v86, v87 offset0:164 offset1:230
	v_add_u32_e32 v4, 0x1400, v70
	s_waitcnt vmcnt(10)
	ds_write2_b32 v4, v88, v89 offset0:40 offset1:106
	s_waitcnt vmcnt(8)
	ds_write2_b32 v4, v90, v54 offset0:172 offset1:238
	v_add_u32_e32 v4, 0x1800, v70
	s_waitcnt vmcnt(6)
	ds_write2_b32 v4, v40, v41 offset0:48 offset1:114
	s_waitcnt vmcnt(4)
	ds_write2_b32 v4, v42, v43 offset0:180 offset1:246
	v_add_u32_e32 v4, 0x1c00, v70
	s_waitcnt vmcnt(2)
	ds_write2_b32 v4, v44, v45 offset0:56 offset1:122
	s_waitcnt vmcnt(0)
	ds_write2_b32 v4, v46, v38 offset0:188 offset1:254
	s_waitcnt lgkmcnt(0)
	ds_read2_b32 v[42:43], v77 offset1:16
	ds_read2_b32 v[44:45], v77 offset0:33 offset1:49
	ds_read2_b32 v[46:47], v77 offset0:66 offset1:82
	ds_read2_b32 v[50:51], v77 offset0:99 offset1:115
	v_mov_b32_e32 v38, v5
	s_waitcnt lgkmcnt(3)
	v_mul_f32_e32 v4, 0x42800000, v42
	s_waitcnt lgkmcnt(2)
	v_mul_f32_e32 v39, 0x42800000, v44
	v_cvt_pk_fp8_f32 v38, v4, v39
	ds_read2_b32 v[52:53], v77 offset0:132 offset1:148
	ds_read2_b32 v[54:55], v77 offset0:165 offset1:181
	ds_read2_b32 v[56:57], v77 offset0:198 offset1:214
	s_waitcnt lgkmcnt(4)
	v_mul_f32_e32 v40, 0x42800000, v46
	s_waitcnt lgkmcnt(3)
	v_mul_f32_e32 v4, 0x42800000, v50
	v_cvt_pk_fp8_f32 v38, v40, v4 op_sel:[0,0,1]
	s_waitcnt lgkmcnt(2)
	v_mul_f32_e32 v4, 0x42800000, v52
	s_waitcnt lgkmcnt(1)
	v_mul_f32_e32 v40, 0x42800000, v54
	v_mov_b32_e32 v39, v5
	ds_read2_b32 v[58:59], v77 offset0:231 offset1:247
	v_cvt_pk_fp8_f32 v39, v4, v40
	v_add_u32_e32 v4, 0x400, v77
	ds_read2_b32 v[60:61], v4 offset0:8 offset1:24
	ds_read2_b32 v[62:63], v4 offset0:41 offset1:57
	ds_read2_b32 v[64:65], v4 offset0:74 offset1:90
	ds_read2_b32 v[66:67], v4 offset0:107 offset1:123
	ds_read2_b32 v[68:69], v4 offset0:140 offset1:156
	ds_read2_b32 v[84:85], v4 offset0:173 offset1:189
	s_waitcnt lgkmcnt(7)
	v_mul_f32_e32 v41, 0x42800000, v56
	s_waitcnt lgkmcnt(6)
	v_mul_f32_e32 v40, 0x42800000, v58
	v_cvt_pk_fp8_f32 v39, v41, v40 op_sel:[0,0,1]
	s_waitcnt lgkmcnt(5)
	v_mul_f32_e32 v41, 0x42800000, v60
	s_waitcnt lgkmcnt(4)
	v_mul_f32_e32 v42, 0x42800000, v62
	v_mov_b32_e32 v40, v5
	ds_read2_b32 v[86:87], v4 offset0:206 offset1:222
	ds_read2_b32 v[88:89], v4 offset0:239 offset1:255
	v_cvt_pk_fp8_f32 v40, v41, v42
	s_waitcnt lgkmcnt(3)
	v_mul_f32_e32 v42, 0x42800000, v68
	s_waitcnt lgkmcnt(2)
	v_mul_f32_e32 v50, 0x42800000, v84
	v_mov_b32_e32 v41, v5
	v_cvt_pk_fp8_f32 v41, v42, v50
	v_mul_f32_e32 v44, 0x42800000, v64
	v_mul_f32_e32 v46, 0x42800000, v66
	s_waitcnt lgkmcnt(1)
	v_mul_f32_e32 v4, 0x42800000, v86
	s_waitcnt lgkmcnt(0)
	v_mul_f32_e32 v42, 0x42800000, v88
	v_cvt_pk_fp8_f32 v40, v44, v46 op_sel:[0,0,1]
	v_cvt_pk_fp8_f32 v41, v4, v42 op_sel:[0,0,1]
	v_or_b32_e32 v4, s4, v76
	v_lshl_add_u64 v[48:49], v[18:19], 0, s[0:1]
	v_lshlrev_b32_e32 v4, 12, v4
	v_lshl_add_u64 v[90:91], v[48:49], 0, v[4:5]
	global_store_dwordx4 v[90:91], v[38:41], off nt
	v_mul_f32_e32 v4, 0x42800000, v43
	v_mul_f32_e32 v42, 0x42800000, v55
	v_mul_f32_e32 v39, 0x42800000, v45
	v_mov_b32_e32 v38, v5
	v_cvt_pk_fp8_f32 v38, v4, v39
	v_mul_f32_e32 v4, 0x42800000, v53
	v_mov_b32_e32 v39, v5
	v_cvt_pk_fp8_f32 v39, v4, v42
	v_mul_f32_e32 v40, 0x42800000, v47
	v_mul_f32_e32 v41, 0x42800000, v51
	v_cvt_pk_fp8_f32 v38, v40, v41 op_sel:[0,0,1]
	v_mul_f32_e32 v4, 0x42800000, v57
	v_mul_f32_e32 v40, 0x42800000, v59
	v_cvt_pk_fp8_f32 v39, v4, v40 op_sel:[0,0,1]
	v_mul_f32_e32 v4, 0x42800000, v61
	v_mul_f32_e32 v41, 0x42800000, v63
	v_mov_b32_e32 v40, v5
	v_cvt_pk_fp8_f32 v40, v4, v41
	v_mul_f32_e32 v4, 0x42800000, v69
	v_mul_f32_e32 v44, 0x42800000, v85
	v_mov_b32_e32 v41, v5
	v_cvt_pk_fp8_f32 v41, v4, v44
	v_mul_f32_e32 v42, 0x42800000, v65
	v_mul_f32_e32 v43, 0x42800000, v67
	v_cvt_pk_fp8_f32 v40, v42, v43 op_sel:[0,0,1]
	v_mul_f32_e32 v4, 0x42800000, v87
	v_mul_f32_e32 v42, 0x42800000, v89
	v_cvt_pk_fp8_f32 v41, v4, v42 op_sel:[0,0,1]
	v_or_b32_e32 v4, s4, v78
	v_lshlrev_b32_e32 v4, 12, v4
	v_lshl_add_u64 v[42:43], v[48:49], 0, v[4:5]
	global_store_dwordx4 v[42:43], v[38:41], off nt
	s_waitcnt lgkmcnt(0)

; #define LAS __attribute__((address_space(3)))
; __device__ __forceinline__ unsigned pack4_fp8(float a, float b, float c, float d) { unsigned w = 0u; w = (unsigned)__builtin_amdgcn_cvt_pk_fp8_f32(a, b, (int)w, false); w = (unsigned)__builtin_amdgcn_cvt_pk_fp8_f32(c, d, (int)w, true); return w; }
; template <bool F8 = false, class Map>
; __device__ __forceinline__ void transpose_item(const float* __restrict__ W, int Nsrc, int K, void* WTv, const float* kscale, float mul, LAS float* scr, int kb, int nb, int lane, const Map map) {
;     ...
;     for (int i = 0; i < 32; ++i) scr[(2 * i + kh) * 33 + (lane & 31)] = v[i];
;     asm volatile("s_waitcnt lgkmcnt(0)" ::: "memory");
;     if constexpr (F8) {
;         unsigned char* WT = (unsigned char*)WTv; const int c = lane & 3;
; #pragma unroll
;         for (int jj = 0; jj < 2; ++jj) { const int n = (lane >> 2) + 16 * jj; const LAS float* s = scr + (16 * c) * 33 + n;
;             u32x4 o; o.x = pack4_fp8(s[0 * 33] * mul, s[1 * 33] * mul, s[2 * 33] * mul, s[3 * 33] * mul); o.y = pack4_fp8(s[4 * 33] * mul, s[5 * 33] * mul, s[6 * 33] * mul, s[7 * 33] * mul);
;             o.z = pack4_fp8(s[8 * 33] * mul, s[9 * 33] * mul, s[10 * 33] * mul, s[11 * 33] * mul); o.w = pack4_fp8(s[12 * 33] * mul, s[13 * 33] * mul, s[14 * 33] * mul, s[15 * 33] * mul);
;             *(u32x4*)(WT + (size_t)(j0 + n) * K + k0 + 16 * c) = o; }
; __device__ __forceinline__ void p0_prologue(Frame& F) {
;     ...
;             if (r < I_IN) { int kb, nb; blk8(r, 64, kb, nb); transpose_item<FP8_IN>(F.w_in, 7280, D, (void*)(ws + WS_WINT), nullptr, FP8_IN ? 64.f : 1.f, scr, kb, nb, lane, MapWin{}); continue; } r -= I_IN;
.LBB0_280:
	s_or_b64 exec, exec, s[10:11]
	v_add_u32_e32 v4, 0x400, v70
	s_waitcnt vmcnt(0)
	ds_write2_b32 v70, v40, v41 offset1:66
	ds_write2_b32 v70, v43, v42 offset0:132 offset1:198
	ds_write2_b32 v4, v45, v44 offset0:8 offset1:74
	ds_write2_b32 v4, v47, v46 offset0:140 offset1:206
	v_add_u32_e32 v4, 0x800, v70
	ds_write2_b32 v4, v49, v48 offset0:16 offset1:82
	ds_write2_b32 v4, v51, v50 offset0:148 offset1:214
	v_add_u32_e32 v4, 0xc00, v70
	ds_write2_b32 v4, v53, v52 offset0:24 offset1:90
	ds_write2_b32 v4, v55, v54 offset0:156 offset1:222
	v_add_u32_e32 v4, 0x1000, v70
	ds_write2_b32 v4, v57, v56 offset0:32 offset1:98
	ds_write2_b32 v4, v59, v58 offset0:164 offset1:230
	v_add_u32_e32 v4, 0x1400, v70
	ds_write2_b32 v4, v61, v60 offset0:40 offset1:106
	ds_write2_b32 v4, v63, v62 offset0:172 offset1:238
	v_add_u32_e32 v4, 0x1800, v70
	ds_write2_b32 v4, v65, v64 offset0:48 offset1:114
	ds_write2_b32 v4, v67, v66 offset0:180 offset1:246
	v_add_u32_e32 v4, 0x1c00, v70
	ds_write2_b32 v4, v69, v68 offset0:56 offset1:122
	ds_write2_b32 v4, v84, v83 offset0:188 offset1:254
	s_waitcnt lgkmcnt(0)
	ds_read2_b32 v[42:43], v77 offset1:16
	ds_read2_b32 v[44:45], v77 offset0:33 offset1:49
	ds_read2_b32 v[46:47], v77 offset0:66 offset1:82
	ds_read2_b32 v[50:51], v77 offset0:99 offset1:115
	v_mov_b32_e32 v38, v5
	s_waitcnt lgkmcnt(3)
	v_mul_f32_e32 v4, 0x42800000, v42
	s_waitcnt lgkmcnt(2)
	v_mul_f32_e32 v39, 0x42800000, v44
	v_cvt_pk_fp8_f32 v38, v4, v39
	ds_read2_b32 v[52:53], v77 offset0:132 offset1:148
	ds_read2_b32 v[54:55], v77 offset0:165 offset1:181
	ds_read2_b32 v[56:57], v77 offset0:198 offset1:214
	s_waitcnt lgkmcnt(4)
	v_mul_f32_e32 v40, 0x42800000, v46
	s_waitcnt lgkmcnt(3)
	v_mul_f32_e32 v4, 0x42800000, v50
	v_cvt_pk_fp8_f32 v38, v40, v4 op_sel:[0,0,1]
	s_waitcnt lgkmcnt(2)
	v_mul_f32_e32 v4, 0x42800000, v52
	s_waitcnt lgkmcnt(1)
	v_mul_f32_e32 v40, 0x42800000, v54
	v_mov_b32_e32 v39, v5
	ds_read2_b32 v[58:59], v77 offset0:231 offset1:247
	v_cvt_pk_fp8_f32 v39, v4, v40
	v_add_u32_e32 v4, 0x400, v77
	ds_read2_b32 v[60:61], v4 offset0:8 offset1:24
	ds_read2_b32 v[62:63], v4 offset0:41 offset1:57
	ds_read2_b32 v[64:65], v4 offset0:74 offset1:90
	ds_read2_b32 v[66:67], v4 offset0:107 offset1:123
	ds_read2_b32 v[68:69], v4 offset0:140 offset1:156
	ds_read2_b32 v[84:85], v4 offset0:173 offset1:189
	s_waitcnt lgkmcnt(7)
	v_mul_f32_e32 v41, 0x42800000, v56
	s_waitcnt lgkmcnt(6)
	v_mul_f32_e32 v40, 0x42800000, v58
	v_cvt_pk_fp8_f32 v39, v41, v40 op_sel:[0,0,1]
	s_waitcnt lgkmcnt(5)
	v_mul_f32_e32 v41, 0x42800000, v60
	s_waitcnt lgkmcnt(4)
	v_mul_f32_e32 v42, 0x42800000, v62
	v_mov_b32_e32 v40, v5
	ds_read2_b32 v[86:87], v4 offset0:206 offset1:222
	ds_read2_b32 v[88:89], v4 offset0:239 offset1:255
	v_cvt_pk_fp8_f32 v40, v41, v42
	s_waitcnt lgkmcnt(3)
	v_mul_f32_e32 v42, 0x42800000, v68
	s_waitcnt lgkmcnt(2)
	v_mul_f32_e32 v50, 0x42800000, v84
	v_mov_b32_e32 v41, v5
	v_cvt_pk_fp8_f32 v41, v42, v50
	v_mul_f32_e32 v44, 0x42800000, v64
	v_mul_f32_e32 v46, 0x42800000, v66
	s_waitcnt lgkmcnt(1)
	v_mul_f32_e32 v4, 0x42800000, v86
	s_waitcnt lgkmcnt(0)
	v_mul_f32_e32 v42, 0x42800000, v88
	v_cvt_pk_fp8_f32 v40, v44, v46 op_sel:[0,0,1]
	v_cvt_pk_fp8_f32 v41, v4, v42 op_sel:[0,0,1]
	v_or_b32_e32 v4, s12, v76
	v_lshl_add_u64 v[48:49], v[20:21], 0, s[0:1]
	v_lshlrev_b32_e32 v4, 12, v4
	v_lshl_add_u64 v[90:91], v[48:49], 0, v[4:5]
	global_store_dwordx4 v[90:91], v[38:41], off nt
	v_mul_f32_e32 v4, 0x42800000, v43
	v_mul_f32_e32 v42, 0x42800000, v55
	v_mul_f32_e32 v39, 0x42800000, v45
	v_mov_b32_e32 v38, v5
	v_cvt_pk_fp8_f32 v38, v4, v39
	v_mul_f32_e32 v4, 0x42800000, v53
	v_mov_b32_e32 v39, v5
	v_cvt_pk_fp8_f32 v39, v4, v42
	v_mul_f32_e32 v40, 0x42800000, v47
	v_mul_f32_e32 v41, 0x42800000, v51
	v_cvt_pk_fp8_f32 v38, v40, v41 op_sel:[0,0,1]
	v_mul_f32_e32 v4, 0x42800000, v57
	v_mul_f32_e32 v40, 0x42800000, v59
	v_cvt_pk_fp8_f32 v39, v4, v40 op_sel:[0,0,1]
	v_mul_f32_e32 v4, 0x42800000, v61
	v_mul_f32_e32 v41, 0x42800000, v63
	v_mov_b32_e32 v40, v5
	v_cvt_pk_fp8_f32 v40, v4, v41
	v_mul_f32_e32 v4, 0x42800000, v69
	v_mul_f32_e32 v44, 0x42800000, v85
	v_mov_b32_e32 v41, v5
	v_cvt_pk_fp8_f32 v41, v4, v44
	v_mul_f32_e32 v42, 0x42800000, v65
	v_mul_f32_e32 v43, 0x42800000, v67
	v_cvt_pk_fp8_f32 v40, v42, v43 op_sel:[0,0,1]
	v_mul_f32_e32 v4, 0x42800000, v87
	v_mul_f32_e32 v42, 0x42800000, v89
	v_cvt_pk_fp8_f32 v41, v4, v42 op_sel:[0,0,1]
	v_or_b32_e32 v4, s12, v78
	v_lshlrev_b32_e32 v4, 12, v4
	v_lshl_add_u64 v[42:43], v[48:49], 0, v[4:5]
	global_store_dwordx4 v[42:43], v[38:41], off nt
	s_waitcnt lgkmcnt(0)

; #define LAS __attribute__((address_space(3)))
; template <bool F8 = false, class Map>
; __device__ __forceinline__ void transpose_item(const float* __restrict__ W, int Nsrc, int K, void* WTv, const float* kscale, float mul, LAS float* scr, int kb, int nb, int lane, const Map map) {
;     const int k0 = 64 * kb, j0 = 32 * nb, sc = map(j0 + (lane & 31)), kh = lane >> 5;
;     float v[32];
; #pragma unroll
;     for (int i = 0; i < 32; ++i) v[i] = sc >= 0 ? W[(size_t)(k0 + 2 * i + kh) * Nsrc + sc] : 0.f;
; __device__ __forceinline__ void p0_prologue(Frame& F) {
;     ...
;             if (r < I_F2) { int kb, nb; blk16(r, 256, kb, nb); transpose_item(F.w_ff2, D, DFF, (bf16_t*)(ws + WS_WFF2T), nullptr, 1.f, scr, kb, nb, lane, MapId{}); continue; } r -= I_F2;
.LBB0_282:
	s_andn2_b64 vcc, exec, s[4:5]
	s_cbranch_vccnz .LBB0_284
	s_lshr_b32 s0, s58, 8
	s_and_b32 s0, s0, 0xf0
	s_and_b32 s4, s58, 15
	s_or_b32 s4, s0, s4
	s_lshl_b32 s4, s4, 5
	s_and_b32 s0, s19, 0x3fc0
	v_bitop3_b32 v4, s4, v1, v82 bitop3:0xde
	v_readlane_b32 s60, v245, 10
	v_or_b32_e32 v40, s0, v3
	v_lshlrev_b32_e32 v4, 2, v4
	v_readlane_b32 s68, v245, 18
	v_readlane_b32 s69, v245, 19
	s_lshl_b32 s0, s0, 1
	v_readlane_b32 s61, v245, 11
	v_lshl_add_u64 v[38:39], s[68:69], 0, v[4:5]
	v_lshlrev_b32_e32 v4, 14, v40
	v_lshl_add_u64 v[38:39], v[38:39], 0, v[4:5]
	v_add_co_u32_e32 v40, vcc, s22, v38
	v_readlane_b32 s62, v245, 12
	s_nop 0
	v_addc_co_u32_e32 v41, vcc, 0, v39, vcc
	v_add_co_u32_e32 v42, vcc, s23, v38
	v_readlane_b32 s63, v245, 13
	s_nop 0
	v_addc_co_u32_e32 v43, vcc, 0, v39, vcc
	v_add_co_u32_e32 v44, vcc, s24, v38
	v_readlane_b32 s64, v245, 14
	s_nop 0
	v_addc_co_u32_e32 v45, vcc, 0, v39, vcc
	v_add_co_u32_e32 v46, vcc, s25, v38
	v_readlane_b32 s65, v245, 15
	s_nop 0
	v_addc_co_u32_e32 v47, vcc, 0, v39, vcc
	v_add_co_u32_e32 v48, vcc, s26, v38
	v_readlane_b32 s66, v245, 16
	s_nop 0
	v_addc_co_u32_e32 v49, vcc, 0, v39, vcc
	v_add_co_u32_e32 v50, vcc, s27, v38
	v_readlane_b32 s67, v245, 17
	s_nop 0
	v_addc_co_u32_e32 v51, vcc, 0, v39, vcc
	v_add_co_u32_e32 v52, vcc, s28, v38
	v_readlane_b32 s70, v245, 20
	s_nop 0
	v_addc_co_u32_e32 v53, vcc, 0, v39, vcc
	global_load_dword v4, v[38:39], off
	global_load_dword v56, v[40:41], off
	global_load_dword v57, v[42:43], off
	global_load_dword v58, v[44:45], off
	global_load_dword v59, v[46:47], off
	global_load_dword v60, v[48:49], off
	global_load_dword v61, v[50:51], off
	global_load_dword v62, v[52:53], off
	v_add_co_u32_e32 v40, vcc, s29, v38
	v_readlane_b32 s71, v245, 21
	s_nop 0
	v_addc_co_u32_e32 v41, vcc, 0, v39, vcc
	v_add_co_u32_e32 v42, vcc, s33, v38
	v_readlane_b32 s72, v245, 22
	s_nop 0
	v_addc_co_u32_e32 v43, vcc, 0, v39, vcc
	v_add_co_u32_e32 v44, vcc, s34, v38
	v_readlane_b32 s73, v245, 23
	s_nop 0
	v_addc_co_u32_e32 v45, vcc, 0, v39, vcc
	v_add_co_u32_e32 v46, vcc, s36, v38
	v_readlane_b32 s74, v245, 24
	s_nop 0
	v_addc_co_u32_e32 v47, vcc, 0, v39, vcc
	v_add_co_u32_e32 v48, vcc, s38, v38
	v_readlane_b32 s75, v245, 25
	s_nop 0
	v_addc_co_u32_e32 v49, vcc, 0, v39, vcc
	v_add_co_u32_e32 v50, vcc, s39, v38
	s_nop 1
	v_addc_co_u32_e32 v51, vcc, 0, v39, vcc
	v_add_co_u32_e32 v52, vcc, s40, v38
	s_nop 1
	v_addc_co_u32_e32 v53, vcc, 0, v39, vcc
	v_add_co_u32_e32 v54, vcc, s41, v38
	s_nop 1
	v_addc_co_u32_e32 v55, vcc, 0, v39, vcc
	global_load_dword v63, v[40:41], off
	global_load_dword v64, v[42:43], off
	global_load_dword v65, v[44:45], off
	global_load_dword v66, v[46:47], off
	global_load_dword v67, v[48:49], off
	global_load_dword v68, v[50:51], off
	global_load_dword v69, v[52:53], off
	global_load_dword v83, v[54:55], off
	v_add_co_u32_e32 v40, vcc, s42, v38
	s_nop 1
	v_addc_co_u32_e32 v41, vcc, 0, v39, vcc
	v_add_co_u32_e32 v42, vcc, s43, v38
	s_nop 1
	v_addc_co_u32_e32 v43, vcc, 0, v39, vcc
	v_add_co_u32_e32 v44, vcc, s44, v38
	s_nop 1
	v_addc_co_u32_e32 v45, vcc, 0, v39, vcc
	v_add_co_u32_e32 v46, vcc, s45, v38
	s_nop 1
	v_addc_co_u32_e32 v47, vcc, 0, v39, vcc
	v_add_co_u32_e32 v48, vcc, s46, v38
	s_nop 1
	v_addc_co_u32_e32 v49, vcc, 0, v39, vcc
	v_add_co_u32_e32 v50, vcc, s47, v38
	s_nop 1
	v_addc_co_u32_e32 v51, vcc, 0, v39, vcc
	v_add_co_u32_e32 v52, vcc, s48, v38
	s_nop 1
	v_addc_co_u32_e32 v53, vcc, 0, v39, vcc
	v_add_co_u32_e32 v54, vcc, s49, v38
	s_nop 1
	v_addc_co_u32_e32 v55, vcc, 0, v39, vcc
	global_load_dword v84, v[40:41], off
	global_load_dword v85, v[42:43], off
	global_load_dword v86, v[44:45], off
	global_load_dword v87, v[46:47], off
	global_load_dword v88, v[48:49], off
	global_load_dword v89, v[50:51], off
	global_load_dword v90, v[52:53], off
	s_nop 0
	global_load_dword v54, v[54:55], off
	v_add_co_u32_e32 v40, vcc, s50, v38
	s_nop 1
	v_addc_co_u32_e32 v41, vcc, 0, v39, vcc
	v_add_co_u32_e32 v42, vcc, s51, v38
	s_nop 1
	v_addc_co_u32_e32 v43, vcc, 0, v39, vcc
	v_add_co_u32_e32 v44, vcc, s52, v38
	s_nop 1
	v_addc_co_u32_e32 v45, vcc, 0, v39, vcc
	v_add_co_u32_e32 v46, vcc, s53, v38
	s_nop 1
	v_addc_co_u32_e32 v47, vcc, 0, v39, vcc
	v_add_co_u32_e32 v48, vcc, s54, v38
	s_nop 1
	v_addc_co_u32_e32 v49, vcc, 0, v39, vcc
	v_add_co_u32_e32 v50, vcc, s55, v38
	s_nop 1
	v_addc_co_u32_e32 v51, vcc, 0, v39, vcc
	v_add_co_u32_e32 v52, vcc, s56, v38
	s_nop 1
	v_addc_co_u32_e32 v53, vcc, 0, v39, vcc
	v_add_co_u32_e32 v38, vcc, s57, v38
	s_nop 1
	v_addc_co_u32_e32 v39, vcc, 0, v39, vcc
	global_load_dword v40, v[40:41], off
	s_nop 0
	global_load_dword v41, v[42:43], off
	s_nop 0
	global_load_dword v42, v[44:45], off
	global_load_dword v43, v[46:47], off
	s_nop 0
	global_load_dword v44, v[48:49], off
	global_load_dword v45, v[50:51], off
	global_load_dword v46, v[52:53], off
	s_nop 0
	global_load_dword v38, v[38:39], off
	s_waitcnt vmcnt(30)
; #define LAS __attribute__((address_space(3)))
; __device__ __forceinline__ unsigned cvtpk(float lo, float hi) { f32x2 v = {lo, hi}; bf16x2_t b = __builtin_convertvector(v, bf16x2_t); return __builtin_bit_cast(unsigned, b); }
; __device__ __forceinline__ unsigned pack4_fp8(float a, float b, float c, float d) { unsigned w = 0u; w = (unsigned)__builtin_amdgcn_cvt_pk_fp8_f32(a, b, (int)w, false); w = (unsigned)__builtin_amdgcn_cvt_pk_fp8_f32(c, d, (int)w, true); return w; }
; template <bool F8 = false, class Map>
; __device__ __forceinline__ void transpose_item(const float* __restrict__ W, int Nsrc, int K, void* WTv, const float* kscale, float mul, LAS float* scr, int kb, int nb, int lane, const Map map) {
;     ...
;     for (int i = 0; i < 32; ++i) scr[(2 * i + kh) * 33 + (lane & 31)] = v[i];
;     asm volatile("s_waitcnt lgkmcnt(0)" ::: "memory");
;     if constexpr (F8) {
;         unsigned char* WT = (unsigned char*)WTv; const int c = lane & 3;
; #pragma unroll
;         for (int jj = 0; jj < 2; ++jj) { const int n = (lane >> 2) + 16 * jj; const LAS float* s = scr + (16 * c) * 33 + n;
;             u32x4 o; o.x = pack4_fp8(s[0 * 33] * mul, s[1 * 33] * mul, s[2 * 33] * mul, s[3 * 33] * mul); o.y = pack4_fp8(s[4 * 33] * mul, s[5 * 33] * mul, s[6 * 33] * mul, s[7 * 33] * mul);
;             o.z = pack4_fp8(s[8 * 33] * mul, s[9 * 33] * mul, s[10 * 33] * mul, s[11 * 33] * mul); o.w = pack4_fp8(s[12 * 33] * mul, s[13 * 33] * mul, s[14 * 33] * mul, s[15 * 33] * mul);
;             *(u32x4*)(WT + (size_t)(j0 + n) * K + k0 + 16 * c) = o; }
;     } else {
;         bf16_t* WT = (bf16_t*)WTv; const int c = lane & 7;
; #pragma unroll
;         for (int jj = 0; jj < 4; ++jj) { const int n = (lane >> 3) + 8 * jj; const LAS float* s = scr + (8 * c) * 33 + n;
;             u32x4 o; o.x = cvtpk(s[0 * 33], s[1 * 33]); o.y = cvtpk(s[2 * 33], s[3 * 33]); o.z = cvtpk(s[4 * 33], s[5 * 33]); o.w = cvtpk(s[6 * 33], s[7 * 33]);
;             *(u32x4*)(WT + (size_t)(j0 + n) * K + k0 + 8 * c) = o; }
;     }
	ds_write2_b32 v70, v4, v56 offset1:66
	s_waitcnt vmcnt(28)
	ds_write2_b32 v70, v57, v58 offset0:132 offset1:198
	v_add_u32_e32 v4, 0x400, v70
	s_waitcnt vmcnt(26)
	ds_write2_b32 v4, v59, v60 offset0:8 offset1:74
	s_waitcnt vmcnt(24)
	ds_write2_b32 v4, v61, v62 offset0:140 offset1:206
	v_add_u32_e32 v4, 0x800, v70
	s_waitcnt vmcnt(22)
	ds_write2_b32 v4, v63, v64 offset0:16 offset1:82
	s_waitcnt vmcnt(20)
	ds_write2_b32 v4, v65, v66 offset0:148 offset1:214
	v_add_u32_e32 v4, 0xc00, v70
	s_waitcnt vmcnt(18)
	ds_write2_b32 v4, v67, v68 offset0:24 offset1:90
	s_waitcnt vmcnt(16)
	ds_write2_b32 v4, v69, v83 offset0:156 offset1:222
	v_add_u32_e32 v4, 0x1000, v70
	s_waitcnt vmcnt(14)
	ds_write2_b32 v4, v84, v85 offset0:32 offset1:98
	s_waitcnt vmcnt(12)
	ds_write2_b32 v4, v86, v87 offset0:164 offset1:230
	v_add_u32_e32 v4, 0x1400, v70
	s_waitcnt vmcnt(10)
	ds_write2_b32 v4, v88, v89 offset0:40 offset1:106
	s_waitcnt vmcnt(8)
	ds_write2_b32 v4, v90, v54 offset0:172 offset1:238
	v_add_u32_e32 v4, 0x1800, v70
	s_waitcnt vmcnt(6)
	ds_write2_b32 v4, v40, v41 offset0:48 offset1:114
	s_waitcnt vmcnt(4)
	ds_write2_b32 v4, v42, v43 offset0:180 offset1:246
	v_add_u32_e32 v4, 0x1c00, v70
	s_waitcnt vmcnt(2)
	ds_write2_b32 v4, v44, v45 offset0:56 offset1:122
	s_waitcnt vmcnt(0)
	ds_write2_b32 v4, v46, v38 offset0:188 offset1:254
	s_waitcnt lgkmcnt(0)
	ds_read2_b32 v[42:43], v72 offset0:33 offset1:41
	ds_read2_b32 v[44:45], v72 offset1:8
	ds_read2_b32 v[46:47], v72 offset0:66 offset1:74
	ds_read2_b32 v[48:49], v72 offset0:99 offset1:107
	ds_read2_b32 v[50:51], v72 offset0:132 offset1:140
	ds_read2_b32 v[52:53], v72 offset0:165 offset1:173
	ds_read2_b32 v[54:55], v72 offset0:198 offset1:206
	ds_read2_b32 v[56:57], v72 offset0:231 offset1:239
	v_bitop3_b32 v4, s4, v71, v82 bitop3:0xde
	v_lshl_add_u64 v[58:59], v[22:23], 0, s[0:1]
	v_lshlrev_b32_e32 v4, 15, v4
	s_waitcnt lgkmcnt(6)
	v_cvt_pk_bf16_f32 v38, v44, v42
	s_waitcnt lgkmcnt(4)
	v_cvt_pk_bf16_f32 v39, v46, v48
	s_waitcnt lgkmcnt(2)
	v_cvt_pk_bf16_f32 v40, v50, v52
	s_waitcnt lgkmcnt(0)
	v_cvt_pk_bf16_f32 v41, v54, v56
	v_lshl_add_u64 v[60:61], v[58:59], 0, v[4:5]
	global_store_dwordx4 v[60:61], v[38:41], off nt
	v_bitop3_b32 v4, s4, v73, v82 bitop3:0xde
	v_lshlrev_b32_e32 v4, 15, v4
	v_cvt_pk_bf16_f32 v38, v45, v43
	v_cvt_pk_bf16_f32 v39, v47, v49
	v_cvt_pk_bf16_f32 v40, v51, v53
	v_cvt_pk_bf16_f32 v41, v55, v57
	ds_read2_b32 v[44:45], v72 offset0:49 offset1:57
	ds_read2_b32 v[46:47], v72 offset0:16 offset1:24
	ds_read2_b32 v[48:49], v72 offset0:82 offset1:90
	ds_read2_b32 v[50:51], v72 offset0:115 offset1:123
	ds_read2_b32 v[52:53], v72 offset0:148 offset1:156
	ds_read2_b32 v[54:55], v72 offset0:181 offset1:189
	ds_read2_b32 v[56:57], v72 offset0:214 offset1:222
	ds_read2_b32 v[60:61], v72 offset0:247 offset1:255
	v_lshl_add_u64 v[42:43], v[58:59], 0, v[4:5]
	v_bitop3_b32 v4, s4, v74, v82 bitop3:0xde
	v_lshlrev_b32_e32 v4, 15, v4
	global_store_dwordx4 v[42:43], v[38:41], off nt
	v_lshl_add_u64 v[42:43], v[58:59], 0, v[4:5]
	v_bitop3_b32 v4, s4, v75, v82 bitop3:0xde
	s_waitcnt lgkmcnt(6)
	v_cvt_pk_bf16_f32 v38, v46, v44
	s_waitcnt lgkmcnt(4)
	v_cvt_pk_bf16_f32 v39, v48, v50
	s_waitcnt lgkmcnt(2)
	v_cvt_pk_bf16_f32 v40, v52, v54
	s_waitcnt lgkmcnt(0)
	v_cvt_pk_bf16_f32 v41, v56, v60
	v_lshlrev_b32_e32 v4, 15, v4
	global_store_dwordx4 v[42:43], v[38:41], off nt
	v_lshl_add_u64 v[42:43], v[58:59], 0, v[4:5]
	s_nop 0
	v_cvt_pk_bf16_f32 v38, v47, v45
	v_cvt_pk_bf16_f32 v39, v49, v51
	v_cvt_pk_bf16_f32 v40, v53, v55
	v_cvt_pk_bf16_f32 v41, v57, v61
	global_store_dwordx4 v[42:43], v[38:41], off nt
	s_waitcnt lgkmcnt(0)
